# 128x128 GEMM loops (out-proj, FFN-out): 4-stage LDS ring, one workgroup barrier per two K steps
# speedup vs baseline: 1.1013x; 1.0087x over previous
.LBB0_1406:
	s_cmp_lt_u32 s26, 10
	s_cselect_b32 s0, s41, s43
	v_mov_b32_e32 v79, s0
	s_movk_i32 s0, 0x180
	s_cselect_b32 s0, s0, 0x500
	v_mad_i64_i32 v[80:81], s[30:31], s0, v64, 0
	s_cselect_b32 s29, s40, s42
	s_cselect_b32 s30, 0, 0xfffffe80
	v_mov_b32_e32 v78, s29
	s_cselect_b32 s29, 0, -1
	s_add_u32 s30, s10, s30
	v_lshl_add_u64 v[78:79], v[80:81], 1, v[78:79]
	s_addc_u32 s31, s11, s29
	v_lshl_add_u64 v[78:79], s[30:31], 1, v[78:79]
	s_lshl_b32 s29, s28, 14
	s_waitcnt vmcnt(0)
	v_lshl_add_u64 v[82:83], v[78:79], 0, v[68:69]
	s_add_i32 s29, s14, s29
	s_lshl_b32 s0, s0, 5
	s_waitcnt lgkmcnt(0)
	s_barrier
	v_lshl_add_u64 v[78:79], v[82:83], 0, s[4:5]
	s_mov_b32 m0, s29
	v_lshl_add_u64 v[120:121], v[82:83], 0, s[0:1]
	global_load_lds_dwordx4 v[78:79], off
	v_lshl_add_u64 v[78:79], v[120:121], 0, s[4:5]
	s_add_i32 m0, s29, 0x400
	v_lshl_add_u64 v[122:123], v[66:67], 0, s[12:13]
	global_load_lds_dwordx4 v[78:79], off
	s_add_i32 m0, s29, 0x2000
	v_lshl_add_u64 v[78:79], v[122:123], 0, s[4:5]
	s_lshl_b32 s0, s27, 14
	global_load_lds_dwordx4 v[78:79], off
	s_add_i32 m0, s29, 0x2400
	v_add_u32_e32 v65, s0, v88
	v_or_b32_e32 v124, s0, v89
	s_add_i32 s0, s27, 1
	s_cmp_lg_u32 s27, 3
	s_mov_b64 s[30:31], 0x8080
	s_cselect_b32 s27, s0, 0
	s_add_i32 s0, s28, 1
	v_lshl_add_u64 v[78:79], v[122:123], 0, s[30:31]
	s_cmp_lg_u32 s28, 3
	global_load_lds_dwordx4 v[78:79], off
	s_cselect_b32 s0, s0, 0
	ds_read_b128 v[78:81], v65
	ds_read_b128 v[92:95], v65 offset:1024
	ds_read_b128 v[96:99], v65 offset:2048
	ds_read_b128 v[100:103], v65 offset:3072
	ds_read_b128 v[104:107], v124
	ds_read_b128 v[108:111], v124 offset:1024
	ds_read_b128 v[112:115], v124 offset:2048
	ds_read_b128 v[116:119], v124 offset:3072
	s_waitcnt lgkmcnt(0)
	s_lshl_b32 s28, s0, 14
	s_add_i32 s30, s14, s28
	v_mfma_f32_16x16x32_bf16 v[60:63], v[104:107], v[78:81], v[60:63]
	v_mfma_f32_16x16x32_bf16 v[56:59], v[108:111], v[78:81], v[56:59]
	s_mov_b32 m0, s30
	s_mov_b64 s[28:29], 0x80c0
	s_add_i32 s26, s26, 2
	v_mfma_f32_16x16x32_bf16 v[52:55], v[112:115], v[78:81], v[52:55]
	v_mfma_f32_16x16x32_bf16 v[48:51], v[116:119], v[78:81], v[48:51]
	v_lshl_add_u64 v[78:79], v[82:83], 0, s[6:7]
	global_load_lds_dwordx4 v[78:79], off
	v_lshl_add_u64 v[78:79], v[120:121], 0, s[6:7]
	s_add_i32 m0, s30, 0x400
	v_mfma_f32_16x16x32_bf16 v[44:47], v[104:107], v[92:95], v[44:47]
	global_load_lds_dwordx4 v[78:79], off
	s_add_i32 m0, s30, 0x2000
	v_lshl_add_u64 v[78:79], v[122:123], 0, s[6:7]
	global_load_lds_dwordx4 v[78:79], off
	v_lshl_add_u64 v[78:79], v[122:123], 0, s[28:29]
	s_add_i32 m0, s30, 0x2400
	s_lshl_b32 s28, s27, 14
	global_load_lds_dwordx4 v[78:79], off
	v_add_u32_e32 v65, s28, v88
	v_or_b32_e32 v82, s28, v89
	s_add_i32 s28, s27, 1
	v_mfma_f32_16x16x32_bf16 v[40:43], v[108:111], v[92:95], v[40:43]
	s_cmp_lg_u32 s27, 3
	s_cselect_b32 s27, s28, 0
	s_add_i32 s28, s0, 1
	v_mfma_f32_16x16x32_bf16 v[36:39], v[112:115], v[92:95], v[36:39]
	s_cmp_lg_u32 s0, 3
	s_cselect_b32 s28, s28, 0
	s_add_u32 s12, s12, 0x80
	v_mfma_f32_16x16x32_bf16 v[32:35], v[116:119], v[92:95], v[32:35]
	s_addc_u32 s13, s13, 0
	s_add_u32 s10, s10, 64
	s_addc_u32 s11, s11, 0
	v_mfma_f32_16x16x32_bf16 v[28:31], v[104:107], v[96:99], v[28:31]
	s_cmpk_eq_i32 s12, 0x780
	v_mfma_f32_16x16x32_bf16 v[24:27], v[108:111], v[96:99], v[24:27]
	v_mfma_f32_16x16x32_bf16 v[20:23], v[112:115], v[96:99], v[20:23]
	v_mfma_f32_16x16x32_bf16 v[16:19], v[116:119], v[96:99], v[16:19]
	v_mfma_f32_16x16x32_bf16 v[12:15], v[104:107], v[100:103], v[12:15]
	v_mfma_f32_16x16x32_bf16 v[8:11], v[108:111], v[100:103], v[8:11]
	v_mfma_f32_16x16x32_bf16 v[4:7], v[112:115], v[100:103], v[4:7]
	v_mfma_f32_16x16x32_bf16 v[0:3], v[116:119], v[100:103], v[0:3]
	ds_read_b128 v[78:81], v65
	ds_read_b128 v[92:95], v65 offset:1024
	ds_read_b128 v[96:99], v65 offset:2048
	ds_read_b128 v[100:103], v65 offset:3072
	ds_read_b128 v[104:107], v82
	ds_read_b128 v[108:111], v82 offset:1024
	ds_read_b128 v[112:115], v82 offset:2048
	ds_read_b128 v[116:119], v82 offset:3072
	s_waitcnt lgkmcnt(0)
	s_nop 0
	v_mfma_f32_16x16x32_bf16 v[60:63], v[104:107], v[78:81], v[60:63]
	v_mfma_f32_16x16x32_bf16 v[56:59], v[108:111], v[78:81], v[56:59]
	v_mfma_f32_16x16x32_bf16 v[52:55], v[112:115], v[78:81], v[52:55]
	v_mfma_f32_16x16x32_bf16 v[48:51], v[116:119], v[78:81], v[48:51]
	v_mfma_f32_16x16x32_bf16 v[44:47], v[104:107], v[92:95], v[44:47]
	v_mfma_f32_16x16x32_bf16 v[40:43], v[108:111], v[92:95], v[40:43]
	v_mfma_f32_16x16x32_bf16 v[36:39], v[112:115], v[92:95], v[36:39]
	v_mfma_f32_16x16x32_bf16 v[32:35], v[116:119], v[92:95], v[32:35]
	v_mfma_f32_16x16x32_bf16 v[28:31], v[104:107], v[96:99], v[28:31]
	v_mfma_f32_16x16x32_bf16 v[24:27], v[108:111], v[96:99], v[24:27]
	v_mfma_f32_16x16x32_bf16 v[20:23], v[112:115], v[96:99], v[20:23]
	v_mfma_f32_16x16x32_bf16 v[16:19], v[116:119], v[96:99], v[16:19]
	v_mfma_f32_16x16x32_bf16 v[12:15], v[104:107], v[100:103], v[12:15]
	v_mfma_f32_16x16x32_bf16 v[8:11], v[108:111], v[100:103], v[8:11]
	v_mfma_f32_16x16x32_bf16 v[4:7], v[112:115], v[100:103], v[4:7]
	v_mfma_f32_16x16x32_bf16 v[0:3], v[116:119], v[100:103], v[0:3]
	s_cbranch_scc0 .LBB0_1406
	s_waitcnt vmcnt(4)
	s_waitcnt lgkmcnt(0)
	s_barrier
	ds_read_b128 v[64:67], v88 offset:32768
	ds_read_b128 v[78:81], v88 offset:33792
	ds_read_b128 v[92:95], v88 offset:34816
	ds_read_b128 v[96:99], v88 offset:35840
	ds_read_b128 v[100:103], v89 offset:32768
	ds_read_b128 v[104:107], v89 offset:33792
	ds_read_b128 v[108:111], v89 offset:34816
	ds_read_b128 v[112:115], v89 offset:35840
	s_waitcnt lgkmcnt(0)
	s_waitcnt vmcnt(0)
	s_waitcnt lgkmcnt(0)
	s_barrier
	v_mfma_f32_16x16x32_bf16 v[56:59], v[104:107], v[64:67], v[56:59]
	s_movk_i32 s0, 0xfff
	v_readlane_b32 s36, v241, 1
	v_mfma_f32_16x16x32_bf16 v[40:43], v[104:107], v[78:81], v[40:43]
	v_readlane_b32 s44, v241, 9
	v_readlane_b32 s45, v241, 10
	s_add_i32 s2, s2, s3
	v_mfma_f32_16x16x32_bf16 v[24:27], v[104:107], v[92:95], v[24:27]
	s_add_i32 s15, s15, s16
	s_cmpk_gt_i32 s2, 0x9f
	v_readlane_b32 s37, v241, 2
	v_mfma_f32_16x16x32_bf16 v[52:55], v[108:111], v[64:67], v[52:55]
	v_readlane_b32 s38, v241, 3
	v_readlane_b32 s39, v241, 4
	v_readlane_b32 s40, v241, 5
	v_mfma_f32_16x16x32_bf16 v[36:39], v[108:111], v[78:81], v[36:39]
	v_readlane_b32 s41, v241, 6
	v_readlane_b32 s42, v241, 7
	v_readlane_b32 s43, v241, 8
	v_mfma_f32_16x16x32_bf16 v[20:23], v[108:111], v[92:95], v[20:23]
	v_readlane_b32 s46, v241, 11
	v_readlane_b32 s47, v241, 12
	v_readlane_b32 s48, v241, 13
	v_mfma_f32_16x16x32_bf16 v[60:63], v[100:103], v[64:67], v[60:63]
	v_readlane_b32 s49, v241, 14
	v_readlane_b32 s50, v241, 15
	v_readlane_b32 s51, v241, 16
	v_mfma_f32_16x16x32_bf16 v[48:51], v[112:115], v[64:67], v[48:51]
	v_mfma_f32_16x16x32_bf16 v[44:47], v[100:103], v[78:81], v[44:47]
	v_mfma_f32_16x16x32_bf16 v[32:35], v[112:115], v[78:81], v[32:35]
	v_mfma_f32_16x16x32_bf16 v[28:31], v[100:103], v[92:95], v[28:31]
	v_mfma_f32_16x16x32_bf16 v[16:19], v[112:115], v[92:95], v[16:19]
	v_mfma_f32_16x16x32_bf16 v[12:15], v[100:103], v[96:99], v[12:15]
	v_mfma_f32_16x16x32_bf16 v[8:11], v[104:107], v[96:99], v[8:11]
	v_mfma_f32_16x16x32_bf16 v[4:7], v[108:111], v[96:99], v[4:7]
	v_mfma_f32_16x16x32_bf16 v[0:3], v[112:115], v[96:99], v[0:3]
	ds_read_b128 v[64:67], v88 offset:49152
	ds_read_b128 v[78:81], v88 offset:50176
	ds_read_b128 v[92:95], v88 offset:51200
	ds_read_b128 v[96:99], v88 offset:52224
	ds_read_b128 v[100:103], v89 offset:49152
	ds_read_b128 v[104:107], v89 offset:50176
	ds_read_b128 v[108:111], v89 offset:51200
	ds_read_b128 v[112:115], v89 offset:52224
	s_waitcnt lgkmcnt(0)
	s_waitcnt lgkmcnt(0)
	s_barrier
	v_mfma_f32_16x16x32_bf16 v[120:123], v[104:107], v[64:67], v[56:59]
	v_mfma_f32_16x16x32_bf16 v[56:59], v[104:107], v[78:81], v[40:43]
	v_mfma_f32_16x16x32_bf16 v[40:43], v[104:107], v[92:95], v[24:27]
	s_nop 2
	v_add_u32_e32 v24, s24, v86
	v_mfma_f32_16x16x32_bf16 v[124:127], v[108:111], v[64:67], v[52:55]
	v_cmp_lt_i32_e32 vcc, s0, v24
	s_movk_i32 s0, 0x6000
	v_mfma_f32_16x16x32_bf16 v[52:55], v[108:111], v[78:81], v[36:39]
	v_mfma_f32_16x16x32_bf16 v[36:39], v[108:111], v[92:95], v[20:23]
	s_nop 2
	v_add_u32_e32 v21, 0xfffff000, v24
	v_lshrrev_b32_e32 v21, 12, v21
	v_add_u32_e32 v21, 1, v21
	v_or_b32_e32 v20, s25, v87
	v_cndmask_b32_e32 v21, 0, v21, vcc
	v_mad_u64_u32 v[22:23], s[10:11], v21, s0, v[74:75]
	v_ashrrev_i32_e32 v21, 31, v20
	v_mfma_f32_16x16x32_bf16 v[116:119], v[100:103], v[64:67], v[60:63]
	s_mov_b64 s[10:11], 0x2000
	s_movk_i32 s0, 0x2000
	v_mfma_f32_16x16x32_bf16 v[64:67], v[112:115], v[64:67], v[48:51]
	v_mfma_f32_16x16x32_bf16 v[60:63], v[100:103], v[78:81], v[44:47]
	v_mfma_f32_16x16x32_bf16 v[48:51], v[112:115], v[78:81], v[32:35]
	v_lshlrev_b64 v[78:79], 2, v[20:21]
	v_lshl_add_u64 v[20:21], v[22:23], 0, v[78:79]
	v_lshl_add_u64 v[20:21], v[20:21], 0, v[76:77]
	v_lshl_add_u64 v[22:23], v[20:21], 0, s[10:11]
	v_add_co_u32_e32 v20, vcc, s0, v20
	v_mfma_f32_16x16x32_bf16 v[44:47], v[100:103], v[92:95], v[28:31]
	s_nop 0
	v_addc_co_u32_e32 v21, vcc, 0, v21, vcc
	v_mfma_f32_16x16x32_bf16 v[16:19], v[112:115], v[92:95], v[16:19]
	v_or_b32_e32 v92, v24, v84
	v_or_b32_e32 v82, 32, v92
	v_or_b32_e32 v80, 48, v92
	v_mfma_f32_16x16x32_bf16 v[12:15], v[100:103], v[96:99], v[12:15]
	global_load_dwordx4 v[32:35], v[20:21], off
	global_load_dwordx4 v[28:31], v[22:23], off offset:64
	global_load_dwordx4 v[24:27], v[22:23], off offset:128
	s_nop 0
	global_load_dwordx4 v[20:23], v[22:23], off offset:192
	v_mfma_f32_16x16x32_bf16 v[8:11], v[104:107], v[96:99], v[8:11]
	v_mfma_f32_16x16x32_bf16 v[4:7], v[108:111], v[96:99], v[4:7]
	v_mfma_f32_16x16x32_bf16 v[0:3], v[112:115], v[96:99], v[0:3]
	v_or_b32_e32 v96, 16, v92
	s_nop 0
	v_ashrrev_i32_e32 v93, 31, v92
	v_lshlrev_b64 v[92:93], 12, v[92:93]
	v_lshl_add_u64 v[92:93], s[44:45], 0, v[92:93]
	v_lshl_add_u64 v[92:93], v[92:93], 0, v[78:79]
	v_lshl_add_u64 v[98:99], v[92:93], 0, v[76:77]
	global_load_dwordx4 v[92:95], v[98:99], off
	s_waitcnt vmcnt(0)
	v_pk_mul_f32 v[92:93], v[92:93], s[8:9] op_sel_hi:[1,0]
	v_pk_mul_f32 v[94:95], v[94:95], s[8:9] op_sel_hi:[1,0]
	v_pk_fma_f32 v[92:93], v[116:117], v[32:33], v[92:93]
	v_pk_fma_f32 v[94:95], v[118:119], v[34:35], v[94:95]
	global_store_dwordx4 v[98:99], v[92:95], off
	global_load_dwordx4 v[92:95], v[98:99], off offset:64
	s_waitcnt vmcnt(0)
	v_pk_mul_f32 v[92:93], v[92:93], s[8:9] op_sel_hi:[1,0]
	v_pk_mul_f32 v[94:95], v[94:95], s[8:9] op_sel_hi:[1,0]
	v_pk_fma_f32 v[92:93], v[120:121], v[28:29], v[92:93]
	v_pk_fma_f32 v[94:95], v[122:123], v[30:31], v[94:95]
	global_store_dwordx4 v[98:99], v[92:95], off offset:64
	global_load_dwordx4 v[92:95], v[98:99], off offset:128
	s_waitcnt vmcnt(0)
	v_pk_mul_f32 v[92:93], v[92:93], s[8:9] op_sel_hi:[1,0]
	v_pk_mul_f32 v[94:95], v[94:95], s[8:9] op_sel_hi:[1,0]
	v_pk_fma_f32 v[92:93], v[124:125], v[24:25], v[92:93]
	v_pk_fma_f32 v[94:95], v[126:127], v[26:27], v[94:95]
	global_store_dwordx4 v[98:99], v[92:95], off offset:128
	global_load_dwordx4 v[92:95], v[98:99], off offset:192
	s_waitcnt vmcnt(0)
	v_pk_mul_f32 v[92:93], v[92:93], s[8:9] op_sel_hi:[1,0]
	s_nop 0
	v_pk_fma_f32 v[64:65], v[64:65], v[20:21], v[92:93]
	v_pk_mul_f32 v[92:93], v[94:95], s[8:9] op_sel_hi:[1,0]
	s_nop 0
	v_pk_fma_f32 v[66:67], v[66:67], v[22:23], v[92:93]
	global_store_dwordx4 v[98:99], v[64:67], off offset:192
	s_nop 0
	v_ashrrev_i32_e32 v97, 31, v96
	v_lshlrev_b64 v[64:65], 12, v[96:97]
	v_lshl_add_u64 v[64:65], s[44:45], 0, v[64:65]
	v_lshl_add_u64 v[64:65], v[64:65], 0, v[78:79]
	v_lshl_add_u64 v[92:93], v[64:65], 0, v[76:77]
	global_load_dwordx4 v[64:67], v[92:93], off
	s_waitcnt vmcnt(0)
	v_pk_mul_f32 v[64:65], v[64:65], s[8:9] op_sel_hi:[1,0]
	s_nop 0
	v_pk_fma_f32 v[60:61], v[60:61], v[32:33], v[64:65]
	v_pk_mul_f32 v[64:65], v[66:67], s[8:9] op_sel_hi:[1,0]
	s_nop 0
	v_pk_fma_f32 v[62:63], v[62:63], v[34:35], v[64:65]
	global_store_dwordx4 v[92:93], v[60:63], off
	global_load_dwordx4 v[60:63], v[92:93], off offset:64
	s_waitcnt vmcnt(0)
	v_pk_mul_f32 v[60:61], v[60:61], s[8:9] op_sel_hi:[1,0]
	s_nop 0
	v_pk_fma_f32 v[56:57], v[56:57], v[28:29], v[60:61]
	v_pk_mul_f32 v[60:61], v[62:63], s[8:9] op_sel_hi:[1,0]
	s_nop 0
	v_pk_fma_f32 v[58:59], v[58:59], v[30:31], v[60:61]
	global_store_dwordx4 v[92:93], v[56:59], off offset:64
	global_load_dwordx4 v[56:59], v[92:93], off offset:128
	s_waitcnt vmcnt(0)
	v_pk_mul_f32 v[56:57], v[56:57], s[8:9] op_sel_hi:[1,0]
	s_nop 0
	v_pk_fma_f32 v[52:53], v[52:53], v[24:25], v[56:57]
	v_pk_mul_f32 v[56:57], v[58:59], s[8:9] op_sel_hi:[1,0]
	s_nop 0
	v_pk_fma_f32 v[54:55], v[54:55], v[26:27], v[56:57]
	global_store_dwordx4 v[92:93], v[52:55], off offset:128
	global_load_dwordx4 v[52:55], v[92:93], off offset:192
	s_waitcnt vmcnt(0)
	v_pk_mul_f32 v[52:53], v[52:53], s[8:9] op_sel_hi:[1,0]
	s_nop 0
	v_pk_fma_f32 v[48:49], v[48:49], v[20:21], v[52:53]
	v_pk_mul_f32 v[52:53], v[54:55], s[8:9] op_sel_hi:[1,0]
	s_nop 0
	v_pk_fma_f32 v[50:51], v[50:51], v[22:23], v[52:53]
	global_store_dwordx4 v[92:93], v[48:51], off offset:192
	s_nop 0
	v_ashrrev_i32_e32 v83, 31, v82
	v_lshlrev_b64 v[48:49], 12, v[82:83]
	v_lshl_add_u64 v[48:49], s[44:45], 0, v[48:49]
	v_lshl_add_u64 v[48:49], v[48:49], 0, v[78:79]
	v_lshl_add_u64 v[52:53], v[48:49], 0, v[76:77]
	global_load_dwordx4 v[48:51], v[52:53], off
	s_waitcnt vmcnt(0)
	v_pk_mul_f32 v[48:49], v[48:49], s[8:9] op_sel_hi:[1,0]
	s_nop 0
	v_pk_fma_f32 v[44:45], v[44:45], v[32:33], v[48:49]
	v_pk_mul_f32 v[48:49], v[50:51], s[8:9] op_sel_hi:[1,0]
	s_nop 0
	v_pk_fma_f32 v[46:47], v[46:47], v[34:35], v[48:49]
	global_store_dwordx4 v[52:53], v[44:47], off
	global_load_dwordx4 v[44:47], v[52:53], off offset:64
	s_waitcnt vmcnt(0)
	v_pk_mul_f32 v[44:45], v[44:45], s[8:9] op_sel_hi:[1,0]
	s_nop 0
	v_pk_fma_f32 v[40:41], v[40:41], v[28:29], v[44:45]
	v_pk_mul_f32 v[44:45], v[46:47], s[8:9] op_sel_hi:[1,0]
	s_nop 0
	v_pk_fma_f32 v[42:43], v[42:43], v[30:31], v[44:45]
	global_store_dwordx4 v[52:53], v[40:43], off offset:64
	global_load_dwordx4 v[40:43], v[52:53], off offset:128
	s_waitcnt vmcnt(0)
	v_pk_mul_f32 v[40:41], v[40:41], s[8:9] op_sel_hi:[1,0]
	s_nop 0
	v_pk_fma_f32 v[36:37], v[36:37], v[24:25], v[40:41]
	v_pk_mul_f32 v[40:41], v[42:43], s[8:9] op_sel_hi:[1,0]
	s_nop 0
	v_pk_fma_f32 v[38:39], v[38:39], v[26:27], v[40:41]
	global_store_dwordx4 v[52:53], v[36:39], off offset:128
	global_load_dwordx4 v[36:39], v[52:53], off offset:192
	s_waitcnt vmcnt(0)
	v_pk_mul_f32 v[36:37], v[36:37], s[8:9] op_sel_hi:[1,0]
	s_nop 0
	v_pk_fma_f32 v[16:17], v[16:17], v[20:21], v[36:37]
	v_pk_mul_f32 v[36:37], v[38:39], s[8:9] op_sel_hi:[1,0]
	s_nop 0
	v_pk_fma_f32 v[18:19], v[18:19], v[22:23], v[36:37]
	global_store_dwordx4 v[52:53], v[16:19], off offset:192
	s_nop 0
	v_ashrrev_i32_e32 v81, 31, v80
	v_lshlrev_b64 v[16:17], 12, v[80:81]
	v_lshl_add_u64 v[16:17], s[44:45], 0, v[16:17]
	v_lshl_add_u64 v[16:17], v[16:17], 0, v[78:79]
	v_lshl_add_u64 v[36:37], v[16:17], 0, v[76:77]
	global_load_dwordx4 v[16:19], v[36:37], off
	s_waitcnt vmcnt(0)
	v_pk_mul_f32 v[16:17], v[16:17], s[8:9] op_sel_hi:[1,0]
	s_nop 0
	v_pk_fma_f32 v[12:13], v[12:13], v[32:33], v[16:17]
	v_pk_mul_f32 v[16:17], v[18:19], s[8:9] op_sel_hi:[1,0]
	s_nop 0
	v_pk_fma_f32 v[14:15], v[14:15], v[34:35], v[16:17]
	global_store_dwordx4 v[36:37], v[12:15], off
	global_load_dwordx4 v[12:15], v[36:37], off offset:64
	s_waitcnt vmcnt(0)
	v_pk_mul_f32 v[12:13], v[12:13], s[8:9] op_sel_hi:[1,0]
	s_nop 0
	v_pk_fma_f32 v[8:9], v[8:9], v[28:29], v[12:13]
	v_pk_mul_f32 v[12:13], v[14:15], s[8:9] op_sel_hi:[1,0]
	s_nop 0
	v_pk_fma_f32 v[10:11], v[10:11], v[30:31], v[12:13]
	global_store_dwordx4 v[36:37], v[8:11], off offset:64
	global_load_dwordx4 v[8:11], v[36:37], off offset:128
	s_waitcnt vmcnt(0)
	v_pk_mul_f32 v[8:9], v[8:9], s[8:9] op_sel_hi:[1,0]
	s_nop 0
	v_pk_fma_f32 v[4:5], v[4:5], v[24:25], v[8:9]
	v_pk_mul_f32 v[8:9], v[10:11], s[8:9] op_sel_hi:[1,0]
	s_nop 0
	v_pk_fma_f32 v[6:7], v[6:7], v[26:27], v[8:9]
	global_store_dwordx4 v[36:37], v[4:7], off offset:128
	global_load_dwordx4 v[4:7], v[36:37], off offset:192
	s_waitcnt vmcnt(0)
	v_pk_mul_f32 v[4:5], v[4:5], s[8:9] op_sel_hi:[1,0]
	s_nop 0
	v_pk_fma_f32 v[0:1], v[0:1], v[20:21], v[4:5]
	v_pk_mul_f32 v[4:5], v[6:7], s[8:9] op_sel_hi:[1,0]
	s_nop 0
	v_pk_fma_f32 v[2:3], v[2:3], v[22:23], v[4:5]
	global_store_dwordx4 v[36:37], v[0:3], off offset:192
	s_cbranch_scc0 .LBB0_1405

.LBB0_1577:
	s_lshl_b32 s36, s35, 14
	s_waitcnt vmcnt(0)
	v_lshl_add_u64 v[80:81], v[66:67], 0, s[16:17]
	s_add_i32 s36, s19, s36
	s_waitcnt lgkmcnt(0)
	s_barrier
	v_lshl_add_u64 v[76:77], v[80:81], 0, s[6:7]
	s_mov_b32 m0, s36
	v_lshl_add_u64 v[118:119], v[64:65], 0, s[16:17]
	global_load_lds_dwordx4 v[76:77], off
	v_lshl_add_u64 v[76:77], v[80:81], 0, s[8:9]
	s_add_i32 m0, s36, 0x400
	s_nop 0
	global_load_lds_dwordx4 v[76:77], off
	s_add_i32 m0, s36, 0x2000
	v_lshl_add_u64 v[76:77], v[118:119], 0, s[6:7]
	global_load_lds_dwordx4 v[76:77], off
	s_add_i32 m0, s36, 0x2400
	s_lshl_b32 s36, s34, 14
	v_add_u32_e32 v120, s36, v86
	v_or_b32_e32 v121, s36, v87
	s_add_i32 s36, s34, 1
	s_cmp_lg_u32 s34, 3
	s_cselect_b32 s34, s36, 0
	s_add_i32 s36, s35, 1
	v_lshl_add_u64 v[76:77], v[118:119], 0, s[8:9]
	s_cmp_lg_u32 s35, 3
	global_load_lds_dwordx4 v[76:77], off
	s_cselect_b32 s35, s36, 0
	ds_read_b128 v[76:79], v120
	ds_read_b128 v[90:93], v120 offset:1024
	ds_read_b128 v[94:97], v120 offset:2048
	ds_read_b128 v[98:101], v120 offset:3072
	ds_read_b128 v[102:105], v121
	ds_read_b128 v[106:109], v121 offset:1024
	ds_read_b128 v[110:113], v121 offset:2048
	ds_read_b128 v[114:117], v121 offset:3072
	s_waitcnt lgkmcnt(0)
	s_lshl_b32 s36, s35, 14
	s_add_i32 s36, s19, s36
	v_mfma_f32_16x16x32_bf16 v[60:63], v[102:105], v[76:79], v[60:63]
	v_mfma_f32_16x16x32_bf16 v[56:59], v[106:109], v[76:79], v[56:59]
	s_mov_b32 m0, s36
	v_mfma_f32_16x16x32_bf16 v[52:55], v[110:113], v[76:79], v[52:55]
	v_mfma_f32_16x16x32_bf16 v[48:51], v[114:117], v[76:79], v[48:51]
	v_lshl_add_u64 v[76:77], v[80:81], 0, s[10:11]
	global_load_lds_dwordx4 v[76:77], off
	v_lshl_add_u64 v[76:77], v[80:81], 0, s[12:13]
	s_add_i32 m0, s36, 0x400
	v_mfma_f32_16x16x32_bf16 v[44:47], v[102:105], v[90:93], v[44:47]
	global_load_lds_dwordx4 v[76:77], off
	s_add_i32 m0, s36, 0x2000
	v_lshl_add_u64 v[76:77], v[118:119], 0, s[10:11]
	global_load_lds_dwordx4 v[76:77], off
	v_lshl_add_u64 v[76:77], v[118:119], 0, s[12:13]
	s_add_i32 m0, s36, 0x2400
	v_mfma_f32_16x16x32_bf16 v[40:43], v[106:109], v[90:93], v[40:43]
	global_load_lds_dwordx4 v[76:77], off
	s_lshl_b32 s36, s34, 14
	v_mfma_f32_16x16x32_bf16 v[36:39], v[110:113], v[90:93], v[36:39]
	v_add_u32_e32 v80, s36, v86
	v_or_b32_e32 v81, s36, v87
	s_add_i32 s36, s34, 1
	v_mfma_f32_16x16x32_bf16 v[32:35], v[114:117], v[90:93], v[32:35]
	s_cmp_lg_u32 s34, 3
	s_cselect_b32 s34, s36, 0
	s_add_i32 s36, s35, 1
	v_mfma_f32_16x16x32_bf16 v[28:31], v[102:105], v[94:97], v[28:31]
	s_cmp_lg_u32 s35, 3
	s_cselect_b32 s35, s36, 0
	s_add_u32 s16, s16, 0x80
	v_mfma_f32_16x16x32_bf16 v[24:27], v[106:109], v[94:97], v[24:27]
	s_addc_u32 s17, s17, 0
	s_cmpk_eq_i32 s16, 0x1580
	v_mfma_f32_16x16x32_bf16 v[20:23], v[110:113], v[94:97], v[20:23]
	v_mfma_f32_16x16x32_bf16 v[16:19], v[114:117], v[94:97], v[16:19]
	v_mfma_f32_16x16x32_bf16 v[12:15], v[102:105], v[98:101], v[12:15]
	v_mfma_f32_16x16x32_bf16 v[8:11], v[106:109], v[98:101], v[8:11]
	v_mfma_f32_16x16x32_bf16 v[4:7], v[110:113], v[98:101], v[4:7]
	v_mfma_f32_16x16x32_bf16 v[0:3], v[114:117], v[98:101], v[0:3]
	ds_read_b128 v[76:79], v80
	ds_read_b128 v[90:93], v80 offset:1024
	ds_read_b128 v[94:97], v80 offset:2048
	ds_read_b128 v[98:101], v80 offset:3072
	ds_read_b128 v[102:105], v81
	ds_read_b128 v[106:109], v81 offset:1024
	ds_read_b128 v[110:113], v81 offset:2048
	ds_read_b128 v[114:117], v81 offset:3072
	s_waitcnt lgkmcnt(0)
	s_nop 0
	v_mfma_f32_16x16x32_bf16 v[60:63], v[102:105], v[76:79], v[60:63]
	v_mfma_f32_16x16x32_bf16 v[56:59], v[106:109], v[76:79], v[56:59]
	v_mfma_f32_16x16x32_bf16 v[52:55], v[110:113], v[76:79], v[52:55]
	v_mfma_f32_16x16x32_bf16 v[48:51], v[114:117], v[76:79], v[48:51]
	v_mfma_f32_16x16x32_bf16 v[44:47], v[102:105], v[90:93], v[44:47]
	v_mfma_f32_16x16x32_bf16 v[40:43], v[106:109], v[90:93], v[40:43]
	v_mfma_f32_16x16x32_bf16 v[36:39], v[110:113], v[90:93], v[36:39]
	v_mfma_f32_16x16x32_bf16 v[32:35], v[114:117], v[90:93], v[32:35]
	v_mfma_f32_16x16x32_bf16 v[28:31], v[102:105], v[94:97], v[28:31]
	v_mfma_f32_16x16x32_bf16 v[24:27], v[106:109], v[94:97], v[24:27]
	v_mfma_f32_16x16x32_bf16 v[20:23], v[110:113], v[94:97], v[20:23]
	v_mfma_f32_16x16x32_bf16 v[16:19], v[114:117], v[94:97], v[16:19]
	v_mfma_f32_16x16x32_bf16 v[12:15], v[102:105], v[98:101], v[12:15]
	v_mfma_f32_16x16x32_bf16 v[8:11], v[106:109], v[98:101], v[8:11]
	v_mfma_f32_16x16x32_bf16 v[4:7], v[110:113], v[98:101], v[4:7]
	v_mfma_f32_16x16x32_bf16 v[0:3], v[114:117], v[98:101], v[0:3]
	s_cbranch_scc0 .LBB0_1577
	s_waitcnt vmcnt(4)
	s_waitcnt lgkmcnt(0)
	s_barrier
	ds_read_b128 v[64:67], v86 offset:32768
	ds_read_b128 v[76:79], v86 offset:33792
	ds_read_b128 v[90:93], v86 offset:34816
	ds_read_b128 v[94:97], v86 offset:35840
	ds_read_b128 v[98:101], v87 offset:32768
	ds_read_b128 v[102:105], v87 offset:33792
	ds_read_b128 v[106:109], v87 offset:34816
	ds_read_b128 v[110:113], v87 offset:35840
	s_waitcnt lgkmcnt(0)
	s_waitcnt vmcnt(0)
	s_waitcnt lgkmcnt(0)
	s_barrier
	v_mfma_f32_16x16x32_bf16 v[56:59], v[102:105], v[64:67], v[56:59]
	s_movk_i32 s16, 0xfff
	v_readlane_b32 s36, v241, 1
	v_mfma_f32_16x16x32_bf16 v[40:43], v[102:105], v[76:79], v[40:43]
	v_readlane_b32 s44, v241, 9
	v_readlane_b32 s45, v241, 10
	s_add_i32 s2, s2, s3
	v_mfma_f32_16x16x32_bf16 v[24:27], v[102:105], v[90:93], v[24:27]
	s_add_i32 s20, s20, s21
	v_readlane_b32 s37, v241, 2
	v_readlane_b32 s38, v241, 3
	v_mfma_f32_16x16x32_bf16 v[52:55], v[106:109], v[64:67], v[52:55]
	v_readlane_b32 s39, v241, 4
	v_readlane_b32 s40, v241, 5
	v_readlane_b32 s41, v241, 6
	v_mfma_f32_16x16x32_bf16 v[36:39], v[106:109], v[76:79], v[36:39]
	v_readlane_b32 s42, v241, 7
	v_readlane_b32 s43, v241, 8
	v_readlane_b32 s46, v241, 11
	v_mfma_f32_16x16x32_bf16 v[20:23], v[106:109], v[90:93], v[20:23]
	v_readlane_b32 s47, v241, 12
	v_readlane_b32 s48, v241, 13
	v_readlane_b32 s49, v241, 14
	v_mfma_f32_16x16x32_bf16 v[60:63], v[98:101], v[64:67], v[60:63]
	v_readlane_b32 s50, v241, 15
	v_readlane_b32 s51, v241, 16
	v_mfma_f32_16x16x32_bf16 v[48:51], v[110:113], v[64:67], v[48:51]
	v_mfma_f32_16x16x32_bf16 v[44:47], v[98:101], v[76:79], v[44:47]
	v_mfma_f32_16x16x32_bf16 v[32:35], v[110:113], v[76:79], v[32:35]
	v_mfma_f32_16x16x32_bf16 v[28:31], v[98:101], v[90:93], v[28:31]
	v_mfma_f32_16x16x32_bf16 v[16:19], v[110:113], v[90:93], v[16:19]
	v_mfma_f32_16x16x32_bf16 v[12:15], v[98:101], v[94:97], v[12:15]
	v_mfma_f32_16x16x32_bf16 v[8:11], v[102:105], v[94:97], v[8:11]
	v_mfma_f32_16x16x32_bf16 v[4:7], v[106:109], v[94:97], v[4:7]
	v_mfma_f32_16x16x32_bf16 v[0:3], v[110:113], v[94:97], v[0:3]
	ds_read_b128 v[64:67], v86 offset:49152
	ds_read_b128 v[76:79], v86 offset:50176
	ds_read_b128 v[90:93], v86 offset:51200
	ds_read_b128 v[94:97], v86 offset:52224
	ds_read_b128 v[98:101], v87 offset:49152
	ds_read_b128 v[102:105], v87 offset:50176
	ds_read_b128 v[106:109], v87 offset:51200
	ds_read_b128 v[110:113], v87 offset:52224
	s_waitcnt lgkmcnt(0)
	s_waitcnt lgkmcnt(0)
	s_barrier
	v_mfma_f32_16x16x32_bf16 v[118:121], v[102:105], v[64:67], v[56:59]
	v_mfma_f32_16x16x32_bf16 v[56:59], v[102:105], v[76:79], v[40:43]
	v_mfma_f32_16x16x32_bf16 v[40:43], v[102:105], v[90:93], v[24:27]
	s_nop 2
	v_add_u32_e32 v24, s31, v84
	v_mfma_f32_16x16x32_bf16 v[122:125], v[106:109], v[64:67], v[52:55]
	v_cmp_lt_i32_e32 vcc, s16, v24
	s_movk_i32 s16, 0x6000
	v_mfma_f32_16x16x32_bf16 v[52:55], v[106:109], v[76:79], v[36:39]
	v_mfma_f32_16x16x32_bf16 v[36:39], v[106:109], v[90:93], v[20:23]
	s_nop 2
	v_add_u32_e32 v21, 0xfffff000, v24
	v_lshrrev_b32_e32 v21, 12, v21
	v_add_u32_e32 v21, 1, v21
	v_or_b32_e32 v20, s33, v85
	v_cndmask_b32_e32 v21, 0, v21, vcc
	v_mad_u64_u32 v[22:23], s[16:17], v21, s16, v[74:75]
	v_ashrrev_i32_e32 v21, 31, v20
	v_mfma_f32_16x16x32_bf16 v[114:117], v[98:101], v[64:67], v[60:63]
	s_mov_b64 s[16:17], 0x5000
	v_mfma_f32_16x16x32_bf16 v[64:67], v[110:113], v[64:67], v[48:51]
	v_mfma_f32_16x16x32_bf16 v[60:63], v[98:101], v[76:79], v[44:47]
	v_mfma_f32_16x16x32_bf16 v[48:51], v[110:113], v[76:79], v[32:35]
	v_lshlrev_b64 v[76:77], 2, v[20:21]
	v_lshl_add_u64 v[20:21], v[22:23], 0, v[76:77]
	v_lshl_add_u64 v[20:21], v[20:21], 0, v[68:69]
	v_lshl_add_u64 v[22:23], v[20:21], 0, s[16:17]
	s_movk_i32 s16, 0x5000
	v_add_co_u32_e32 v20, vcc, s16, v20
	v_mfma_f32_16x16x32_bf16 v[44:47], v[98:101], v[90:93], v[28:31]
	s_nop 0
	v_addc_co_u32_e32 v21, vcc, 0, v21, vcc
	v_mfma_f32_16x16x32_bf16 v[16:19], v[110:113], v[90:93], v[16:19]
	v_or_b32_e32 v90, v24, v82
	v_or_b32_e32 v80, 32, v90
	v_or_b32_e32 v78, 48, v90
	v_mfma_f32_16x16x32_bf16 v[12:15], v[98:101], v[94:97], v[12:15]
	global_load_dwordx4 v[32:35], v[20:21], off
	global_load_dwordx4 v[28:31], v[22:23], off offset:64
	global_load_dwordx4 v[24:27], v[22:23], off offset:128
	s_nop 0
	global_load_dwordx4 v[20:23], v[22:23], off offset:192
	v_mfma_f32_16x16x32_bf16 v[8:11], v[102:105], v[94:97], v[8:11]
	v_mfma_f32_16x16x32_bf16 v[4:7], v[106:109], v[94:97], v[4:7]
	v_mfma_f32_16x16x32_bf16 v[0:3], v[110:113], v[94:97], v[0:3]
	v_or_b32_e32 v94, 16, v90
	s_nop 0
	v_ashrrev_i32_e32 v91, 31, v90
	v_lshlrev_b64 v[90:91], 12, v[90:91]
	v_lshl_add_u64 v[90:91], s[44:45], 0, v[90:91]
	v_lshl_add_u64 v[90:91], v[90:91], 0, v[76:77]
	v_lshl_add_u64 v[96:97], v[90:91], 0, v[68:69]
	global_load_dwordx4 v[90:93], v[96:97], off
	s_waitcnt vmcnt(0)
	v_pk_mul_f32 v[90:91], v[90:91], s[14:15] op_sel_hi:[1,0]
	v_pk_mul_f32 v[92:93], v[92:93], s[14:15] op_sel_hi:[1,0]
	v_pk_fma_f32 v[90:91], v[114:115], v[32:33], v[90:91]
	v_pk_fma_f32 v[92:93], v[116:117], v[34:35], v[92:93]
	global_store_dwordx4 v[96:97], v[90:93], off
	global_load_dwordx4 v[90:93], v[96:97], off offset:64
	s_waitcnt vmcnt(0)
	v_pk_mul_f32 v[90:91], v[90:91], s[14:15] op_sel_hi:[1,0]
	v_pk_mul_f32 v[92:93], v[92:93], s[14:15] op_sel_hi:[1,0]
	v_pk_fma_f32 v[90:91], v[118:119], v[28:29], v[90:91]
	v_pk_fma_f32 v[92:93], v[120:121], v[30:31], v[92:93]
	global_store_dwordx4 v[96:97], v[90:93], off offset:64
	global_load_dwordx4 v[90:93], v[96:97], off offset:128
	s_waitcnt vmcnt(0)
	v_pk_mul_f32 v[90:91], v[90:91], s[14:15] op_sel_hi:[1,0]
	v_pk_mul_f32 v[92:93], v[92:93], s[14:15] op_sel_hi:[1,0]
	v_pk_fma_f32 v[90:91], v[122:123], v[24:25], v[90:91]
	v_pk_fma_f32 v[92:93], v[124:125], v[26:27], v[92:93]
	global_store_dwordx4 v[96:97], v[90:93], off offset:128
	global_load_dwordx4 v[90:93], v[96:97], off offset:192
	s_waitcnt vmcnt(0)
	v_pk_mul_f32 v[90:91], v[90:91], s[14:15] op_sel_hi:[1,0]
	s_nop 0
	v_pk_fma_f32 v[64:65], v[64:65], v[20:21], v[90:91]
	v_pk_mul_f32 v[90:91], v[92:93], s[14:15] op_sel_hi:[1,0]
	s_nop 0
	v_pk_fma_f32 v[66:67], v[66:67], v[22:23], v[90:91]
	global_store_dwordx4 v[96:97], v[64:67], off offset:192
	s_nop 0
	v_ashrrev_i32_e32 v95, 31, v94
	v_lshlrev_b64 v[64:65], 12, v[94:95]
	v_lshl_add_u64 v[64:65], s[44:45], 0, v[64:65]
	v_lshl_add_u64 v[64:65], v[64:65], 0, v[76:77]
	v_lshl_add_u64 v[90:91], v[64:65], 0, v[68:69]
	global_load_dwordx4 v[64:67], v[90:91], off
	s_waitcnt vmcnt(0)
	v_pk_mul_f32 v[64:65], v[64:65], s[14:15] op_sel_hi:[1,0]
	s_nop 0
	v_pk_fma_f32 v[60:61], v[60:61], v[32:33], v[64:65]
	v_pk_mul_f32 v[64:65], v[66:67], s[14:15] op_sel_hi:[1,0]
	s_nop 0
	v_pk_fma_f32 v[62:63], v[62:63], v[34:35], v[64:65]
	global_store_dwordx4 v[90:91], v[60:63], off
	global_load_dwordx4 v[60:63], v[90:91], off offset:64
	s_waitcnt vmcnt(0)
	v_pk_mul_f32 v[60:61], v[60:61], s[14:15] op_sel_hi:[1,0]
	s_nop 0
	v_pk_fma_f32 v[56:57], v[56:57], v[28:29], v[60:61]
	v_pk_mul_f32 v[60:61], v[62:63], s[14:15] op_sel_hi:[1,0]
	s_nop 0
	v_pk_fma_f32 v[58:59], v[58:59], v[30:31], v[60:61]
	global_store_dwordx4 v[90:91], v[56:59], off offset:64
	global_load_dwordx4 v[56:59], v[90:91], off offset:128
	s_waitcnt vmcnt(0)
	v_pk_mul_f32 v[56:57], v[56:57], s[14:15] op_sel_hi:[1,0]
	s_nop 0
	v_pk_fma_f32 v[52:53], v[52:53], v[24:25], v[56:57]
	v_pk_mul_f32 v[56:57], v[58:59], s[14:15] op_sel_hi:[1,0]
	s_nop 0
	v_pk_fma_f32 v[54:55], v[54:55], v[26:27], v[56:57]
	global_store_dwordx4 v[90:91], v[52:55], off offset:128
	global_load_dwordx4 v[52:55], v[90:91], off offset:192
	s_waitcnt vmcnt(0)
	v_pk_mul_f32 v[52:53], v[52:53], s[14:15] op_sel_hi:[1,0]
	s_nop 0
	v_pk_fma_f32 v[48:49], v[48:49], v[20:21], v[52:53]
	v_pk_mul_f32 v[52:53], v[54:55], s[14:15] op_sel_hi:[1,0]
	s_nop 0
	v_pk_fma_f32 v[50:51], v[50:51], v[22:23], v[52:53]
	global_store_dwordx4 v[90:91], v[48:51], off offset:192
	s_nop 0
	v_ashrrev_i32_e32 v81, 31, v80
	v_lshlrev_b64 v[48:49], 12, v[80:81]
	v_lshl_add_u64 v[48:49], s[44:45], 0, v[48:49]
	v_lshl_add_u64 v[48:49], v[48:49], 0, v[76:77]
	v_lshl_add_u64 v[52:53], v[48:49], 0, v[68:69]
	global_load_dwordx4 v[48:51], v[52:53], off
	s_waitcnt vmcnt(0)
	v_pk_mul_f32 v[48:49], v[48:49], s[14:15] op_sel_hi:[1,0]
	s_nop 0
	v_pk_fma_f32 v[44:45], v[44:45], v[32:33], v[48:49]
	v_pk_mul_f32 v[48:49], v[50:51], s[14:15] op_sel_hi:[1,0]
	s_nop 0
	v_pk_fma_f32 v[46:47], v[46:47], v[34:35], v[48:49]
	global_store_dwordx4 v[52:53], v[44:47], off
	global_load_dwordx4 v[44:47], v[52:53], off offset:64
	s_waitcnt vmcnt(0)
	v_pk_mul_f32 v[44:45], v[44:45], s[14:15] op_sel_hi:[1,0]
	s_nop 0
	v_pk_fma_f32 v[40:41], v[40:41], v[28:29], v[44:45]
	v_pk_mul_f32 v[44:45], v[46:47], s[14:15] op_sel_hi:[1,0]
	s_nop 0
	v_pk_fma_f32 v[42:43], v[42:43], v[30:31], v[44:45]
	global_store_dwordx4 v[52:53], v[40:43], off offset:64
	global_load_dwordx4 v[40:43], v[52:53], off offset:128
	s_waitcnt vmcnt(0)
	v_pk_mul_f32 v[40:41], v[40:41], s[14:15] op_sel_hi:[1,0]
	s_nop 0
	v_pk_fma_f32 v[36:37], v[36:37], v[24:25], v[40:41]
	v_pk_mul_f32 v[40:41], v[42:43], s[14:15] op_sel_hi:[1,0]
	s_nop 0
	v_pk_fma_f32 v[38:39], v[38:39], v[26:27], v[40:41]
	global_store_dwordx4 v[52:53], v[36:39], off offset:128
	global_load_dwordx4 v[36:39], v[52:53], off offset:192
	s_waitcnt vmcnt(0)
	v_pk_mul_f32 v[36:37], v[36:37], s[14:15] op_sel_hi:[1,0]
	s_nop 0
	v_pk_fma_f32 v[16:17], v[16:17], v[20:21], v[36:37]
	v_pk_mul_f32 v[36:37], v[38:39], s[14:15] op_sel_hi:[1,0]
	s_nop 0
	v_pk_fma_f32 v[18:19], v[18:19], v[22:23], v[36:37]
	global_store_dwordx4 v[52:53], v[16:19], off offset:192
	s_nop 0
	v_ashrrev_i32_e32 v79, 31, v78
	v_lshlrev_b64 v[16:17], 12, v[78:79]
	v_lshl_add_u64 v[16:17], s[44:45], 0, v[16:17]
	v_lshl_add_u64 v[16:17], v[16:17], 0, v[76:77]
	v_lshl_add_u64 v[36:37], v[16:17], 0, v[68:69]
	global_load_dwordx4 v[16:19], v[36:37], off
	s_waitcnt vmcnt(0)
	v_pk_mul_f32 v[16:17], v[16:17], s[14:15] op_sel_hi:[1,0]
	s_nop 0
	v_pk_fma_f32 v[12:13], v[12:13], v[32:33], v[16:17]
	v_pk_mul_f32 v[16:17], v[18:19], s[14:15] op_sel_hi:[1,0]
	s_nop 0
	v_pk_fma_f32 v[14:15], v[14:15], v[34:35], v[16:17]
	global_store_dwordx4 v[36:37], v[12:15], off
	global_load_dwordx4 v[12:15], v[36:37], off offset:64
	s_waitcnt vmcnt(0)
	v_pk_mul_f32 v[12:13], v[12:13], s[14:15] op_sel_hi:[1,0]
	s_nop 0
	v_pk_fma_f32 v[8:9], v[8:9], v[28:29], v[12:13]
	v_pk_mul_f32 v[12:13], v[14:15], s[14:15] op_sel_hi:[1,0]
	s_nop 0
	v_pk_fma_f32 v[10:11], v[10:11], v[30:31], v[12:13]
	global_store_dwordx4 v[36:37], v[8:11], off offset:64
	global_load_dwordx4 v[8:11], v[36:37], off offset:128
	s_waitcnt vmcnt(0)
	v_pk_mul_f32 v[8:9], v[8:9], s[14:15] op_sel_hi:[1,0]
	s_nop 0
	v_pk_fma_f32 v[4:5], v[4:5], v[24:25], v[8:9]
	v_pk_mul_f32 v[8:9], v[10:11], s[14:15] op_sel_hi:[1,0]
	s_nop 0
	v_pk_fma_f32 v[6:7], v[6:7], v[26:27], v[8:9]
	global_store_dwordx4 v[36:37], v[4:7], off offset:128
	global_load_dwordx4 v[4:7], v[36:37], off offset:192
	s_waitcnt vmcnt(0)
	v_pk_mul_f32 v[4:5], v[4:5], s[14:15] op_sel_hi:[1,0]
	s_nop 0
	v_pk_fma_f32 v[0:1], v[0:1], v[20:21], v[4:5]
	v_pk_mul_f32 v[4:5], v[6:7], s[14:15] op_sel_hi:[1,0]
	s_add_i32 s15, s15, s30
	v_pk_fma_f32 v[2:3], v[2:3], v[22:23], v[4:5]
	s_cmpk_gt_i32 s2, 0x9f
	global_store_dwordx4 v[36:37], v[0:3], off offset:192
	s_cbranch_scc0 .LBB0_1576

.LBB0_2892:
	s_cmp_lt_u32 s46, 10
	s_cselect_b32 s52, s42, 0x500
	s_cselect_b32 s10, s57, s59
	s_cselect_b32 s49, s56, s58
	s_cselect_b32 s54, 0, 0xfffffe80
	v_mad_i64_i32 v[92:93], s[50:51], s52, v64, 0
	s_cselect_b32 s53, 0, -1
	v_mov_b32_e32 v90, s49
	v_mov_b32_e32 v91, s10
	s_add_u32 s50, s24, s54
	v_lshl_add_u64 v[90:91], v[92:93], 1, v[90:91]
	s_addc_u32 s51, s25, s53
	s_lshl_b32 s49, s47, 14
	v_lshl_add_u64 v[90:91], s[50:51], 1, v[90:91]
	s_waitcnt vmcnt(0)
	s_lshl_b32 s10, s52, 5
	s_add_i32 s49, s28, s49
	v_lshl_add_u64 v[120:121], v[90:91], 0, v[68:69]
	s_waitcnt lgkmcnt(0)
	s_barrier
	v_lshl_add_u64 v[90:91], v[120:121], 0, s[12:13]
	v_lshl_add_u64 v[122:123], v[120:121], 0, s[10:11]
	s_mov_b32 m0, s49
	v_lshl_add_u64 v[118:119], v[66:67], 0, s[26:27]
	global_load_lds_dwordx4 v[90:91], off
	v_lshl_add_u64 v[90:91], v[122:123], 0, s[12:13]
	s_add_i32 m0, s49, 0x400
	v_lshl_add_u64 v[78:79], v[118:119], 0, s[12:13]
	global_load_lds_dwordx4 v[90:91], off
	s_add_i32 m0, s49, 0x2000
	s_lshl_b32 s52, s48, 14
	global_load_lds_dwordx4 v[78:79], off
	s_add_i32 m0, s49, 0x2400
	s_add_i32 s10, s48, 1
	s_cmp_lg_u32 s48, 3
	s_cselect_b32 s10, s10, 0
	s_add_i32 s48, s47, 1
	v_lshl_add_u64 v[80:81], v[118:119], 0, s[14:15]
	s_cmp_lg_u32 s47, 3
	global_load_lds_dwordx4 v[80:81], off
	s_cselect_b32 s47, s48, 0
	v_add_u32_e32 v65, s52, v86
	v_or_b32_e32 v124, s52, v87
	ds_read_b128 v[78:81], v65
	ds_read_b128 v[90:93], v65 offset:1024
	ds_read_b128 v[94:97], v65 offset:2048
	ds_read_b128 v[98:101], v65 offset:3072
	ds_read_b128 v[102:105], v124
	ds_read_b128 v[106:109], v124 offset:1024
	ds_read_b128 v[110:113], v124 offset:2048
	ds_read_b128 v[114:117], v124 offset:3072
	s_waitcnt lgkmcnt(0)
	s_lshl_b32 s48, s47, 14
	s_add_i32 s48, s28, s48
	v_mfma_f32_16x16x32_bf16 v[44:47], v[102:105], v[90:93], v[44:47]
	v_mfma_f32_16x16x32_bf16 v[40:43], v[106:109], v[90:93], v[40:43]
	s_mov_b32 m0, s48
	s_add_i32 s46, s46, 2
	v_mfma_f32_16x16x32_bf16 v[36:39], v[110:113], v[90:93], v[36:39]
	v_mfma_f32_16x16x32_bf16 v[32:35], v[114:117], v[90:93], v[32:35]
	v_lshl_add_u64 v[90:91], v[120:121], 0, s[16:17]
	v_lshl_add_u64 v[92:93], v[122:123], 0, s[16:17]
	global_load_lds_dwordx4 v[90:91], off
	s_add_i32 m0, s48, 0x400
	v_mfma_f32_16x16x32_bf16 v[60:63], v[102:105], v[78:81], v[60:63]
	global_load_lds_dwordx4 v[92:93], off
	s_add_i32 m0, s48, 0x2000
	v_mfma_f32_16x16x32_bf16 v[56:59], v[106:109], v[78:81], v[56:59]
	v_mfma_f32_16x16x32_bf16 v[52:55], v[110:113], v[78:81], v[52:55]
	v_mfma_f32_16x16x32_bf16 v[48:51], v[114:117], v[78:81], v[48:51]
	v_lshl_add_u64 v[78:79], v[118:119], 0, s[16:17]
	v_lshl_add_u64 v[80:81], v[118:119], 0, s[18:19]
	global_load_lds_dwordx4 v[78:79], off
	s_add_i32 m0, s48, 0x2400
	s_lshl_b32 s48, s10, 14
	global_load_lds_dwordx4 v[80:81], off
	v_add_u32_e32 v65, s48, v86
	v_or_b32_e32 v118, s48, v87
	s_add_i32 s48, s10, 1
	v_mfma_f32_16x16x32_bf16 v[28:31], v[102:105], v[94:97], v[28:31]
	s_cmp_lg_u32 s10, 3
	s_cselect_b32 s48, s48, 0
	s_add_i32 s10, s47, 1
	v_mfma_f32_16x16x32_bf16 v[20:23], v[106:109], v[94:97], v[20:23]
	s_cmp_lg_u32 s47, 3
	s_cselect_b32 s47, s10, 0
	s_add_u32 s26, s26, 0x80
	v_mfma_f32_16x16x32_bf16 v[16:19], v[110:113], v[94:97], v[16:19]
	s_addc_u32 s27, s27, 0
	s_add_u32 s24, s24, 64
	s_addc_u32 s25, s25, 0
	v_mfma_f32_16x16x32_bf16 v[12:15], v[114:117], v[94:97], v[12:15]
	s_cmpk_eq_i32 s26, 0x780
	v_mfma_f32_16x16x32_bf16 v[8:11], v[102:105], v[98:101], v[8:11]
	v_mfma_f32_16x16x32_bf16 v[4:7], v[106:109], v[98:101], v[4:7]
	v_mfma_f32_16x16x32_bf16 v[0:3], v[110:113], v[98:101], v[0:3]
	v_mfma_f32_16x16x32_bf16 v[24:27], v[114:117], v[98:101], v[24:27]
	ds_read_b128 v[78:81], v65
	ds_read_b128 v[90:93], v65 offset:1024
	ds_read_b128 v[94:97], v65 offset:2048
	ds_read_b128 v[98:101], v65 offset:3072
	ds_read_b128 v[102:105], v118
	ds_read_b128 v[106:109], v118 offset:1024
	ds_read_b128 v[110:113], v118 offset:2048
	ds_read_b128 v[114:117], v118 offset:3072
	s_waitcnt lgkmcnt(0)
	s_nop 0
	v_mfma_f32_16x16x32_bf16 v[60:63], v[102:105], v[78:81], v[60:63]
	v_mfma_f32_16x16x32_bf16 v[56:59], v[106:109], v[78:81], v[56:59]
	v_mfma_f32_16x16x32_bf16 v[52:55], v[110:113], v[78:81], v[52:55]
	v_mfma_f32_16x16x32_bf16 v[48:51], v[114:117], v[78:81], v[48:51]
	v_mfma_f32_16x16x32_bf16 v[44:47], v[102:105], v[90:93], v[44:47]
	v_mfma_f32_16x16x32_bf16 v[40:43], v[106:109], v[90:93], v[40:43]
	v_mfma_f32_16x16x32_bf16 v[36:39], v[110:113], v[90:93], v[36:39]
	v_mfma_f32_16x16x32_bf16 v[32:35], v[114:117], v[90:93], v[32:35]
	v_mfma_f32_16x16x32_bf16 v[28:31], v[102:105], v[94:97], v[28:31]
	v_mfma_f32_16x16x32_bf16 v[20:23], v[106:109], v[94:97], v[20:23]
	v_mfma_f32_16x16x32_bf16 v[16:19], v[110:113], v[94:97], v[16:19]
	v_mfma_f32_16x16x32_bf16 v[12:15], v[114:117], v[94:97], v[12:15]
	v_mfma_f32_16x16x32_bf16 v[8:11], v[102:105], v[98:101], v[8:11]
	v_mfma_f32_16x16x32_bf16 v[4:7], v[106:109], v[98:101], v[4:7]
	v_mfma_f32_16x16x32_bf16 v[0:3], v[110:113], v[98:101], v[0:3]
	v_mfma_f32_16x16x32_bf16 v[24:27], v[114:117], v[98:101], v[24:27]
	s_cbranch_scc0 .LBB0_2892
	s_waitcnt vmcnt(4)
	s_waitcnt lgkmcnt(0)
	s_barrier
	ds_read_b128 v[64:67], v86 offset:32768
	ds_read_b128 v[78:81], v86 offset:33792
	ds_read_b128 v[90:93], v86 offset:34816
	ds_read_b128 v[94:97], v86 offset:35840
	ds_read_b128 v[98:101], v87 offset:32768
	ds_read_b128 v[102:105], v87 offset:33792
	ds_read_b128 v[106:109], v87 offset:34816
	ds_read_b128 v[110:113], v87 offset:35840
	s_waitcnt lgkmcnt(0)
	s_waitcnt vmcnt(0)
	s_waitcnt lgkmcnt(0)
	s_barrier
	v_mfma_f32_16x16x32_bf16 v[158:161], v[102:105], v[90:93], v[20:23]
	s_add_i32 s2, s2, s3
	s_add_i32 s31, s31, s33
	v_mfma_f32_16x16x32_bf16 v[114:117], v[98:101], v[64:67], v[60:63]
	v_add_u32_e32 v22, s44, v84
	v_or_b32_e32 v20, s45, v85
	v_cmp_lt_i32_e32 vcc, s43, v22
	v_mfma_f32_16x16x32_bf16 v[118:121], v[102:105], v[64:67], v[56:59]
	v_ashrrev_i32_e32 v21, 31, v20
	v_readlane_b32 s44, v241, 1
	v_readlane_b32 s52, v241, 9
	v_mfma_f32_16x16x32_bf16 v[122:125], v[106:109], v[64:67], v[52:55]
	v_readlane_b32 s53, v241, 10
	s_cmpk_gt_i32 s2, 0x9f
	v_readlane_b32 s45, v241, 2
	v_mfma_f32_16x16x32_bf16 v[126:129], v[110:113], v[64:67], v[48:51]
	v_readlane_b32 s46, v241, 3
	v_readlane_b32 s47, v241, 4
	v_readlane_b32 s48, v241, 5
	v_mfma_f32_16x16x32_bf16 v[64:67], v[106:109], v[90:93], v[16:19]
	v_readlane_b32 s49, v241, 6
	v_readlane_b32 s50, v241, 7
	v_readlane_b32 s51, v241, 8
	v_add_u32_e32 v16, 0xfffff000, v22
	v_lshrrev_b32_e32 v16, 12, v16
	v_add_u32_e32 v16, 6, v16
	v_mfma_f32_16x16x32_bf16 v[60:63], v[110:113], v[90:93], v[12:15]
	v_readlane_b32 s54, v241, 11
	v_readlane_b32 s55, v241, 12
	v_readlane_b32 s56, v241, 13
	v_cndmask_b32_e32 v12, 5, v16, vcc
	v_mfma_f32_16x16x32_bf16 v[130:133], v[98:101], v[78:81], v[44:47]
	v_mad_u64_u32 v[12:13], s[24:25], v12, s30, v[74:75]
	v_readlane_b32 s57, v241, 14
	v_mfma_f32_16x16x32_bf16 v[134:137], v[102:105], v[78:81], v[40:43]
	v_readlane_b32 s58, v241, 15
	v_readlane_b32 s59, v241, 16
	v_mfma_f32_16x16x32_bf16 v[138:141], v[106:109], v[78:81], v[36:39]
	v_mfma_f32_16x16x32_bf16 v[142:145], v[110:113], v[78:81], v[32:35]
	v_lshlrev_b64 v[78:79], 2, v[20:21]
	v_mfma_f32_16x16x32_bf16 v[52:55], v[98:101], v[94:97], v[8:11]
	s_nop 2
	v_lshl_add_u64 v[8:9], v[12:13], 0, v[78:79]
	v_lshl_add_u64 v[8:9], v[8:9], 0, v[76:77]
	v_mfma_f32_16x16x32_bf16 v[146:149], v[98:101], v[90:93], v[28:31]
	ds_read_b128 v[150:153], v86 offset:49152
	ds_read_b128 v[154:157], v86 offset:50176
	ds_read_b128 v[56:59], v86 offset:51200
	ds_read_b128 v[28:31], v86 offset:52224
	ds_read_b128 v[44:47], v87 offset:49152
	ds_read_b128 v[40:43], v87 offset:50176
	ds_read_b128 v[36:39], v87 offset:51200
	ds_read_b128 v[32:35], v87 offset:52224
	s_waitcnt lgkmcnt(0)
	v_add_co_u32_e32 v14, vcc, s29, v8
	s_waitcnt lgkmcnt(0)
	s_barrier
	v_lshl_add_u64 v[12:13], v[8:9], 0, s[20:21]
	v_or_b32_e32 v98, v22, v82
	v_addc_co_u32_e32 v15, vcc, 0, v9, vcc
	v_mfma_f32_16x16x32_bf16 v[20:23], v[106:109], v[94:97], v[0:3]
	v_or_b32_e32 v162, 16, v98
	v_or_b32_e32 v164, 32, v98
	v_or_b32_e32 v80, 48, v98
	global_load_dwordx4 v[0:3], v[12:13], off offset:64
	global_load_dwordx4 v[8:11], v[12:13], off offset:128
	global_load_dwordx4 v[16:19], v[14:15], off
	s_nop 0
	global_load_dwordx4 v[12:15], v[12:13], off offset:192
	v_mfma_f32_16x16x32_bf16 v[48:51], v[102:105], v[94:97], v[4:7]
	v_ashrrev_i32_e32 v99, 31, v98
	v_mfma_f32_16x16x32_bf16 v[4:7], v[110:113], v[94:97], v[24:27]
	v_lshlrev_b64 v[94:95], 12, v[98:99]
	v_lshl_add_u64 v[98:99], s[52:53], 0, v[94:95]
	v_lshl_add_u64 v[98:99], v[98:99], 0, v[78:79]
	v_lshl_add_u64 v[166:167], v[98:99], 0, v[76:77]
	global_load_dwordx4 v[98:101], v[166:167], off
	v_mfma_f32_16x16x32_bf16 v[90:93], v[40:43], v[150:153], v[118:121]
	global_load_dwordx4 v[106:109], v[166:167], off offset:64
	global_load_dwordx4 v[110:113], v[166:167], off offset:128
	s_waitcnt vmcnt(0)
	v_pk_mul_f32 v[98:99], v[98:99], s[22:23] op_sel_hi:[1,0]
	global_load_dwordx4 v[118:121], v[166:167], off offset:192
	v_mfma_f32_16x16x32_bf16 v[24:27], v[44:47], v[150:153], v[114:117]
	v_mul_f32_e64 v100, v100, s22
	v_mul_f32_e64 v101, v101, s22
	v_pk_mul_f32 v[106:107], v[106:107], s[22:23] op_sel_hi:[1,0]
	v_pk_mul_f32 v[108:109], v[108:109], s[22:23] op_sel_hi:[1,0]
	v_mfma_f32_16x16x32_bf16 v[94:97], v[36:39], v[150:153], v[122:125]
	v_mul_f32_e64 v110, v110, s22
	v_mul_f32_e64 v111, v111, s22
	v_pk_mul_f32 v[112:113], v[112:113], s[22:23] op_sel_hi:[1,0]
	v_pk_fma_f32 v[24:25], v[24:25], v[16:17], v[98:99]
	v_mfma_f32_16x16x32_bf16 v[102:105], v[32:35], v[150:153], v[126:129]
	v_fma_f32 v26, v26, v18, v100
	v_fma_f32 v27, v27, v19, v101
	v_pk_fma_f32 v[90:91], v[90:91], v[0:1], v[106:107]
	v_pk_fma_f32 v[92:93], v[92:93], v[2:3], v[108:109]
	v_pk_fma_f32 v[94:95], v[94:95], v[8:9], v[110:111]
	v_pk_fma_f32 v[96:97], v[96:97], v[10:11], v[112:113]
	v_mfma_f32_16x16x32_bf16 v[114:117], v[44:47], v[154:157], v[130:133]
	s_waitcnt vmcnt(0)
	v_pk_mul_f32 v[118:119], v[118:119], s[22:23] op_sel_hi:[1,0]
	v_pk_mul_f32 v[120:121], v[120:121], s[22:23] op_sel_hi:[1,0]
	v_pk_fma_f32 v[98:99], v[102:103], v[12:13], v[118:119]
	v_pk_fma_f32 v[100:101], v[104:105], v[14:15], v[120:121]
	global_store_dwordx4 v[166:167], v[24:27], off
	global_store_dwordx4 v[166:167], v[90:93], off offset:64
	global_store_dwordx4 v[166:167], v[94:97], off offset:128
	global_store_dwordx4 v[166:167], v[98:101], off offset:192
	v_mfma_f32_16x16x32_bf16 v[122:125], v[40:43], v[154:157], v[134:137]
	v_ashrrev_i32_e32 v163, 31, v162
	v_lshlrev_b64 v[24:25], 12, v[162:163]
	v_lshl_add_u64 v[24:25], s[52:53], 0, v[24:25]
	v_lshl_add_u64 v[24:25], v[24:25], 0, v[78:79]
	v_lshl_add_u64 v[118:119], v[24:25], 0, v[76:77]
	global_load_dwordx4 v[24:27], v[118:119], off
	global_load_dwordx4 v[94:97], v[118:119], off offset:64
	global_load_dwordx4 v[98:101], v[118:119], off offset:128
	global_load_dwordx4 v[106:109], v[118:119], off offset:192
	v_mfma_f32_16x16x32_bf16 v[90:93], v[36:39], v[154:157], v[138:141]
	s_waitcnt vmcnt(0)
	v_pk_mul_f32 v[24:25], v[24:25], s[22:23] op_sel_hi:[1,0]
	v_mfma_f32_16x16x32_bf16 v[102:105], v[32:35], v[154:157], v[142:145]
	v_mul_f32_e64 v26, v26, s22
	v_mul_f32_e64 v27, v27, s22
	v_pk_mul_f32 v[94:95], v[94:95], s[22:23] op_sel_hi:[1,0]
	v_pk_mul_f32 v[96:97], v[96:97], s[22:23] op_sel_hi:[1,0]
	v_pk_mul_f32 v[98:99], v[98:99], s[22:23] op_sel_hi:[1,0]
	v_pk_mul_f32 v[100:101], v[100:101], s[22:23] op_sel_hi:[1,0]
	v_pk_mul_f32 v[106:107], v[106:107], s[22:23] op_sel_hi:[1,0]
	v_pk_mul_f32 v[108:109], v[108:109], s[22:23] op_sel_hi:[1,0]
	v_pk_fma_f32 v[24:25], v[114:115], v[16:17], v[24:25]
	v_pk_fma_f32 v[26:27], v[116:117], v[18:19], v[26:27]
	v_pk_fma_f32 v[94:95], v[122:123], v[0:1], v[94:95]
	v_pk_fma_f32 v[96:97], v[124:125], v[2:3], v[96:97]
	v_pk_fma_f32 v[90:91], v[90:91], v[8:9], v[98:99]
	v_pk_fma_f32 v[92:93], v[92:93], v[10:11], v[100:101]
	v_pk_fma_f32 v[98:99], v[102:103], v[12:13], v[106:107]
	v_pk_fma_f32 v[100:101], v[104:105], v[14:15], v[108:109]
	global_store_dwordx4 v[118:119], v[24:27], off
	global_store_dwordx4 v[118:119], v[94:97], off offset:64
	global_store_dwordx4 v[118:119], v[90:93], off offset:128
	global_store_dwordx4 v[118:119], v[98:101], off offset:192
	v_mfma_f32_16x16x32_bf16 v[110:113], v[44:47], v[56:59], v[146:149]
	v_ashrrev_i32_e32 v165, 31, v164
	v_lshlrev_b64 v[24:25], 12, v[164:165]
	v_lshl_add_u64 v[24:25], s[52:53], 0, v[24:25]
	v_lshl_add_u64 v[24:25], v[24:25], 0, v[78:79]
	v_lshl_add_u64 v[106:107], v[24:25], 0, v[76:77]
	global_load_dwordx4 v[24:27], v[106:107], off
	global_load_dwordx4 v[94:97], v[106:107], off offset:64
	global_load_dwordx4 v[98:101], v[106:107], off offset:128
	global_load_dwordx4 v[102:105], v[106:107], off offset:192
	v_mfma_f32_16x16x32_bf16 v[90:93], v[40:43], v[56:59], v[158:161]
	s_waitcnt vmcnt(0)
	v_pk_mul_f32 v[24:25], v[24:25], s[22:23] op_sel_hi:[1,0]
	v_mfma_f32_16x16x32_bf16 v[64:67], v[36:39], v[56:59], v[64:67]
	v_mul_f32_e64 v26, v26, s22
	v_mul_f32_e64 v27, v27, s22
	v_pk_fma_f32 v[24:25], v[110:111], v[16:17], v[24:25]
	v_pk_fma_f32 v[26:27], v[112:113], v[18:19], v[26:27]
	v_mfma_f32_16x16x32_bf16 v[56:59], v[32:35], v[56:59], v[60:63]
	s_nop 2
	v_mul_f32_e64 v60, v94, s22
	v_mul_f32_e64 v61, v95, s22
	v_pk_mul_f32 v[62:63], v[96:97], s[22:23] op_sel_hi:[1,0]
	v_pk_mul_f32 v[94:95], v[98:99], s[22:23] op_sel_hi:[1,0]
	v_pk_mul_f32 v[96:97], v[100:101], s[22:23] op_sel_hi:[1,0]
	v_pk_mul_f32 v[98:99], v[102:103], s[22:23] op_sel_hi:[1,0]
	v_pk_mul_f32 v[100:101], v[104:105], s[22:23] op_sel_hi:[1,0]
	v_pk_fma_f32 v[60:61], v[90:91], v[0:1], v[60:61]
	v_pk_fma_f32 v[62:63], v[92:93], v[2:3], v[62:63]
	v_pk_fma_f32 v[64:65], v[64:65], v[8:9], v[94:95]
	v_pk_fma_f32 v[66:67], v[66:67], v[10:11], v[96:97]
	v_pk_fma_f32 v[56:57], v[56:57], v[12:13], v[98:99]
	v_pk_fma_f32 v[58:59], v[58:59], v[14:15], v[100:101]
	global_store_dwordx4 v[106:107], v[24:27], off
	global_store_dwordx4 v[106:107], v[60:63], off offset:64
	global_store_dwordx4 v[106:107], v[64:67], off offset:128
	global_store_dwordx4 v[106:107], v[56:59], off offset:192
	v_mfma_f32_16x16x32_bf16 v[44:47], v[44:47], v[28:31], v[52:55]
	v_ashrrev_i32_e32 v81, 31, v80
	v_lshlrev_b64 v[24:25], 12, v[80:81]
	v_lshl_add_u64 v[24:25], s[52:53], 0, v[24:25]
	v_lshl_add_u64 v[24:25], v[24:25], 0, v[78:79]
	v_lshl_add_u64 v[60:61], v[24:25], 0, v[76:77]
	global_load_dwordx4 v[24:27], v[60:61], off
	global_load_dwordx4 v[52:55], v[60:61], off offset:64
	global_load_dwordx4 v[56:59], v[60:61], off offset:128
	v_mfma_f32_16x16x32_bf16 v[40:43], v[40:43], v[28:31], v[48:51]
	s_waitcnt vmcnt(0)
	v_pk_mul_f32 v[24:25], v[24:25], s[22:23] op_sel_hi:[1,0]
	s_nop 0
	global_load_dwordx4 v[48:51], v[60:61], off offset:192
	v_mfma_f32_16x16x32_bf16 v[20:23], v[36:39], v[28:31], v[20:23]
	v_mul_f32_e64 v26, v26, s22
	v_mul_f32_e64 v27, v27, s22
	v_pk_fma_f32 v[16:17], v[44:45], v[16:17], v[24:25]
	v_pk_fma_f32 v[18:19], v[46:47], v[18:19], v[26:27]
	v_mfma_f32_16x16x32_bf16 v[4:7], v[32:35], v[28:31], v[4:7]
	v_mul_f32_e64 v28, v52, s22
	v_mul_f32_e64 v29, v53, s22
	v_pk_mul_f32 v[30:31], v[54:55], s[22:23] op_sel_hi:[1,0]
	v_pk_mul_f32 v[32:33], v[56:57], s[22:23] op_sel_hi:[1,0]
	v_pk_mul_f32 v[34:35], v[58:59], s[22:23] op_sel_hi:[1,0]
	v_pk_fma_f32 v[0:1], v[40:41], v[0:1], v[28:29]
	v_pk_fma_f32 v[2:3], v[42:43], v[2:3], v[30:31]
	v_pk_fma_f32 v[8:9], v[20:21], v[8:9], v[32:33]
	v_pk_fma_f32 v[10:11], v[22:23], v[10:11], v[34:35]
	s_waitcnt vmcnt(0)
	v_pk_mul_f32 v[36:37], v[48:49], s[22:23] op_sel_hi:[1,0]
	v_pk_mul_f32 v[38:39], v[50:51], s[22:23] op_sel_hi:[1,0]
	v_pk_fma_f32 v[4:5], v[4:5], v[12:13], v[36:37]
	v_pk_fma_f32 v[6:7], v[6:7], v[14:15], v[38:39]
	global_store_dwordx4 v[60:61], v[16:19], off
	global_store_dwordx4 v[60:61], v[0:3], off offset:64
	global_store_dwordx4 v[60:61], v[8:11], off offset:128
	global_store_dwordx4 v[60:61], v[4:7], off offset:192
	s_cbranch_scc0 .LBB0_2891

.LBB0_3063:
	s_lshl_b32 s41, s39, 14
	s_waitcnt vmcnt(0)
	v_lshl_add_u64 v[116:117], v[74:75], 0, s[18:19]
	s_add_i32 s41, s21, s41
	s_waitcnt lgkmcnt(0)
	s_barrier
	v_lshl_add_u64 v[84:85], v[116:117], 0, s[6:7]
	s_mov_b32 m0, s41
	v_lshl_add_u64 v[118:119], v[72:73], 0, s[18:19]
	v_lshl_add_u64 v[86:87], v[116:117], 0, s[8:9]
	global_load_lds_dwordx4 v[84:85], off
	s_add_i32 m0, s41, 0x400
	v_lshl_add_u64 v[88:89], v[118:119], 0, s[6:7]
	global_load_lds_dwordx4 v[86:87], off
	s_add_i32 m0, s41, 0x2000
	s_lshl_b32 s42, s40, 14
	global_load_lds_dwordx4 v[88:89], off
	s_add_i32 m0, s41, 0x2400
	s_add_i32 s41, s40, 1
	s_cmp_lg_u32 s40, 3
	s_cselect_b32 s40, s41, 0
	s_add_i32 s41, s39, 1
	v_lshl_add_u64 v[90:91], v[118:119], 0, s[8:9]
	s_cmp_lg_u32 s39, 3
	global_load_lds_dwordx4 v[90:91], off
	s_cselect_b32 s39, s41, 0
	v_add_u32_e32 v120, s42, v80
	v_or_b32_e32 v121, s42, v81
	ds_read_b128 v[84:87], v120
	ds_read_b128 v[88:91], v120 offset:1024
	ds_read_b128 v[92:95], v120 offset:2048
	ds_read_b128 v[96:99], v120 offset:3072
	ds_read_b128 v[100:103], v121
	ds_read_b128 v[104:107], v121 offset:1024
	ds_read_b128 v[108:111], v121 offset:2048
	ds_read_b128 v[112:115], v121 offset:3072
	s_waitcnt lgkmcnt(0)
	s_lshl_b32 s41, s39, 14
	s_add_i32 s41, s21, s41
	v_mfma_f32_16x16x32_bf16 v[60:63], v[100:103], v[84:87], v[60:63]
	v_mfma_f32_16x16x32_bf16 v[56:59], v[104:107], v[84:87], v[56:59]
	s_mov_b32 m0, s41
	v_mfma_f32_16x16x32_bf16 v[52:55], v[108:111], v[84:87], v[52:55]
	v_mfma_f32_16x16x32_bf16 v[48:51], v[112:115], v[84:87], v[48:51]
	v_lshl_add_u64 v[84:85], v[116:117], 0, s[10:11]
	v_lshl_add_u64 v[86:87], v[116:117], 0, s[12:13]
	global_load_lds_dwordx4 v[84:85], off
	s_add_i32 m0, s41, 0x400
	v_mfma_f32_16x16x32_bf16 v[44:47], v[100:103], v[88:91], v[44:47]
	global_load_lds_dwordx4 v[86:87], off
	s_add_i32 m0, s41, 0x2000
	v_mfma_f32_16x16x32_bf16 v[40:43], v[104:107], v[88:91], v[40:43]
	v_mfma_f32_16x16x32_bf16 v[36:39], v[108:111], v[88:91], v[36:39]
	v_mfma_f32_16x16x32_bf16 v[32:35], v[112:115], v[88:91], v[32:35]
	v_lshl_add_u64 v[88:89], v[118:119], 0, s[10:11]
	v_lshl_add_u64 v[90:91], v[118:119], 0, s[12:13]
	global_load_lds_dwordx4 v[88:89], off
	s_add_i32 m0, s41, 0x2400
	v_mfma_f32_16x16x32_bf16 v[28:31], v[100:103], v[92:95], v[28:31]
	global_load_lds_dwordx4 v[90:91], off
	s_lshl_b32 s41, s40, 14
	v_mfma_f32_16x16x32_bf16 v[24:27], v[104:107], v[92:95], v[24:27]
	v_add_u32_e32 v116, s41, v80
	v_or_b32_e32 v117, s41, v81
	s_add_i32 s41, s40, 1
	v_mfma_f32_16x16x32_bf16 v[16:19], v[108:111], v[92:95], v[16:19]
	s_cmp_lg_u32 s40, 3
	s_cselect_b32 s40, s41, 0
	s_add_i32 s41, s39, 1
	v_mfma_f32_16x16x32_bf16 v[12:15], v[112:115], v[92:95], v[12:15]
	s_cmp_lg_u32 s39, 3
	s_cselect_b32 s39, s41, 0
	s_add_u32 s18, s18, 0x80
	v_mfma_f32_16x16x32_bf16 v[8:11], v[100:103], v[96:99], v[8:11]
	s_addc_u32 s19, s19, 0
	s_cmpk_eq_i32 s18, 0x1580
	v_mfma_f32_16x16x32_bf16 v[4:7], v[104:107], v[96:99], v[4:7]
	v_mfma_f32_16x16x32_bf16 v[0:3], v[108:111], v[96:99], v[0:3]
	v_mfma_f32_16x16x32_bf16 v[20:23], v[112:115], v[96:99], v[20:23]
	ds_read_b128 v[84:87], v116
	ds_read_b128 v[88:91], v116 offset:1024
	ds_read_b128 v[92:95], v116 offset:2048
	ds_read_b128 v[96:99], v116 offset:3072
	ds_read_b128 v[100:103], v117
	ds_read_b128 v[104:107], v117 offset:1024
	ds_read_b128 v[108:111], v117 offset:2048
	ds_read_b128 v[112:115], v117 offset:3072
	s_waitcnt lgkmcnt(0)
	s_nop 0
	v_mfma_f32_16x16x32_bf16 v[60:63], v[100:103], v[84:87], v[60:63]
	v_mfma_f32_16x16x32_bf16 v[56:59], v[104:107], v[84:87], v[56:59]
	v_mfma_f32_16x16x32_bf16 v[52:55], v[108:111], v[84:87], v[52:55]
	v_mfma_f32_16x16x32_bf16 v[48:51], v[112:115], v[84:87], v[48:51]
	v_mfma_f32_16x16x32_bf16 v[44:47], v[100:103], v[88:91], v[44:47]
	v_mfma_f32_16x16x32_bf16 v[40:43], v[104:107], v[88:91], v[40:43]
	v_mfma_f32_16x16x32_bf16 v[36:39], v[108:111], v[88:91], v[36:39]
	v_mfma_f32_16x16x32_bf16 v[32:35], v[112:115], v[88:91], v[32:35]
	v_mfma_f32_16x16x32_bf16 v[28:31], v[100:103], v[92:95], v[28:31]
	v_mfma_f32_16x16x32_bf16 v[24:27], v[104:107], v[92:95], v[24:27]
	v_mfma_f32_16x16x32_bf16 v[16:19], v[108:111], v[92:95], v[16:19]
	v_mfma_f32_16x16x32_bf16 v[12:15], v[112:115], v[92:95], v[12:15]
	v_mfma_f32_16x16x32_bf16 v[8:11], v[100:103], v[96:99], v[8:11]
	v_mfma_f32_16x16x32_bf16 v[4:7], v[104:107], v[96:99], v[4:7]
	v_mfma_f32_16x16x32_bf16 v[0:3], v[108:111], v[96:99], v[0:3]
	v_mfma_f32_16x16x32_bf16 v[20:23], v[112:115], v[96:99], v[20:23]
	s_cbranch_scc0 .LBB0_3063
	s_waitcnt vmcnt(4)
	s_waitcnt lgkmcnt(0)
	s_barrier
	ds_read_b128 v[72:75], v80 offset:32768
	ds_read_b128 v[84:87], v80 offset:33792
	ds_read_b128 v[88:91], v80 offset:34816
	ds_read_b128 v[92:95], v80 offset:35840
	ds_read_b128 v[96:99], v81 offset:32768
	ds_read_b128 v[100:103], v81 offset:33792
	ds_read_b128 v[104:107], v81 offset:34816
	ds_read_b128 v[108:111], v81 offset:35840
	s_waitcnt lgkmcnt(0)
	s_waitcnt vmcnt(0)
	s_waitcnt lgkmcnt(0)
	s_barrier
	v_mfma_f32_16x16x32_bf16 v[112:115], v[96:99], v[72:75], v[60:63]
	v_readlane_b32 s40, v241, 1
	v_readlane_b32 s48, v241, 9
	v_mfma_f32_16x16x32_bf16 v[116:119], v[100:103], v[72:75], v[56:59]
	v_readlane_b32 s49, v241, 10
	s_add_i32 s2, s2, s3
	s_add_i32 s22, s22, s23
	v_mfma_f32_16x16x32_bf16 v[120:123], v[104:107], v[72:75], v[52:55]
	v_readlane_b32 s41, v241, 2
	v_readlane_b32 s42, v241, 3
	v_readlane_b32 s43, v241, 4
	v_mfma_f32_16x16x32_bf16 v[124:127], v[108:111], v[72:75], v[48:51]
	v_add_u32_e32 v74, s37, v78
	v_cmp_lt_i32_e32 vcc, s35, v74
	v_readlane_b32 s44, v241, 5
	v_mfma_f32_16x16x32_bf16 v[60:63], v[104:107], v[88:91], v[16:19]
	v_readlane_b32 s45, v241, 6
	v_readlane_b32 s46, v241, 7
	v_readlane_b32 s47, v241, 8
	v_add_u32_e32 v16, 0xfffff000, v74
	v_lshrrev_b32_e32 v16, 12, v16
	v_mfma_f32_16x16x32_bf16 v[152:155], v[100:103], v[88:91], v[24:27]
	v_add_u32_e32 v16, 6, v16
	v_readlane_b32 s50, v241, 11
	v_readlane_b32 s51, v241, 12
	v_or_b32_e32 v24, s38, v79
	v_mfma_f32_16x16x32_bf16 v[56:59], v[108:111], v[88:91], v[12:15]
	v_ashrrev_i32_e32 v25, 31, v24
	v_lshlrev_b64 v[72:73], 2, v[24:25]
	v_readlane_b32 s52, v241, 13
	v_cndmask_b32_e32 v12, 5, v16, vcc
	v_mad_u64_u32 v[12:13], s[18:19], v12, s30, v[70:71]
	v_mfma_f32_16x16x32_bf16 v[48:51], v[96:99], v[92:95], v[8:11]
	v_readlane_b32 s53, v241, 14
	v_readlane_b32 s54, v241, 15
	v_readlane_b32 s55, v241, 16
	v_lshl_add_u64 v[8:9], v[12:13], 0, v[72:73]
	v_lshl_add_u64 v[12:13], v[8:9], 0, v[64:65]
	v_mfma_f32_16x16x32_bf16 v[128:131], v[96:99], v[84:87], v[44:47]
	v_add_co_u32_e32 v18, vcc, s36, v12
	v_lshl_add_u64 v[16:17], v[12:13], 0, s[14:15]
	v_mfma_f32_16x16x32_bf16 v[132:135], v[100:103], v[84:87], v[40:43]
	v_addc_co_u32_e32 v19, vcc, 0, v13, vcc
	v_mfma_f32_16x16x32_bf16 v[136:139], v[104:107], v[84:87], v[36:39]
	v_mfma_f32_16x16x32_bf16 v[84:87], v[108:111], v[84:87], v[32:35]
	v_mfma_f32_16x16x32_bf16 v[140:143], v[96:99], v[88:91], v[28:31]
	ds_read_b128 v[144:147], v80 offset:49152
	ds_read_b128 v[148:151], v80 offset:50176
	ds_read_b128 v[52:55], v80 offset:51200
	ds_read_b128 v[28:31], v80 offset:52224
	ds_read_b128 v[44:47], v81 offset:49152
	ds_read_b128 v[40:43], v81 offset:50176
	ds_read_b128 v[36:39], v81 offset:51200
	ds_read_b128 v[32:35], v81 offset:52224
	s_waitcnt lgkmcnt(0)
	s_waitcnt lgkmcnt(0)
	s_barrier
	v_or_b32_e32 v96, v74, v76
	v_mfma_f32_16x16x32_bf16 v[24:27], v[100:103], v[92:95], v[4:7]
	v_or_b32_e32 v156, 16, v96
	v_or_b32_e32 v158, 32, v96
	v_or_b32_e32 v74, 48, v96
	v_mfma_f32_16x16x32_bf16 v[4:7], v[104:107], v[92:95], v[0:3]
	s_nop 2
	global_load_dwordx4 v[0:3], v[16:17], off offset:64
	global_load_dwordx4 v[12:15], v[16:17], off offset:128
	v_mfma_f32_16x16x32_bf16 v[8:11], v[108:111], v[92:95], v[20:23]
	s_nop 2
	global_load_dwordx4 v[20:23], v[18:19], off
	s_nop 0
	global_load_dwordx4 v[16:19], v[16:17], off offset:192
	s_nop 0
	v_ashrrev_i32_e32 v97, 31, v96
	v_lshlrev_b64 v[96:97], 12, v[96:97]
	v_lshl_add_u64 v[100:101], s[48:49], 0, v[96:97]
	v_lshl_add_u64 v[100:101], v[100:101], 0, v[72:73]
	v_lshl_add_u64 v[160:161], v[100:101], 0, v[64:65]
	global_load_dwordx4 v[100:103], v[160:161], off
	v_mfma_f32_16x16x32_bf16 v[88:91], v[44:47], v[144:147], v[112:115]
	global_load_dwordx4 v[108:111], v[160:161], off offset:64
	s_nop 1
	global_load_dwordx4 v[112:115], v[160:161], off offset:128
	s_waitcnt vmcnt(0)
	v_pk_mul_f32 v[100:101], v[100:101], s[16:17] op_sel_hi:[1,0]
	v_mfma_f32_16x16x32_bf16 v[96:99], v[36:39], v[144:147], v[120:123]
	v_mul_f32_e64 v102, v102, s16
	v_mul_f32_e64 v103, v103, s16
	v_pk_mul_f32 v[108:109], v[108:109], s[16:17] op_sel_hi:[1,0]
	v_pk_mul_f32 v[110:111], v[110:111], s[16:17] op_sel_hi:[1,0]
	global_load_dwordx4 v[120:123], v[160:161], off offset:192
	v_mfma_f32_16x16x32_bf16 v[92:95], v[40:43], v[144:147], v[116:119]
	v_mul_f32_e64 v112, v112, s16
	v_mul_f32_e64 v113, v113, s16
	v_pk_mul_f32 v[114:115], v[114:115], s[16:17] op_sel_hi:[1,0]
	v_pk_fma_f32 v[88:89], v[88:89], v[20:21], v[100:101]
	v_mfma_f32_16x16x32_bf16 v[104:107], v[32:35], v[144:147], v[124:127]
	v_fma_f32 v90, v90, v22, v102
	v_fma_f32 v91, v91, v23, v103
	s_nop 0
	v_pk_fma_f32 v[92:93], v[92:93], v[0:1], v[108:109]
	v_pk_fma_f32 v[94:95], v[94:95], v[2:3], v[110:111]
	v_pk_fma_f32 v[96:97], v[96:97], v[12:13], v[112:113]
	v_pk_fma_f32 v[98:99], v[98:99], v[14:15], v[114:115]
	v_mfma_f32_16x16x32_bf16 v[116:119], v[44:47], v[148:151], v[128:131]
	s_waitcnt vmcnt(0)
	v_pk_mul_f32 v[120:121], v[120:121], s[16:17] op_sel_hi:[1,0]
	v_pk_mul_f32 v[122:123], v[122:123], s[16:17] op_sel_hi:[1,0]
	v_pk_fma_f32 v[100:101], v[104:105], v[16:17], v[120:121]
	v_pk_fma_f32 v[102:103], v[106:107], v[18:19], v[122:123]
	global_store_dwordx4 v[160:161], v[88:91], off
	global_store_dwordx4 v[160:161], v[92:95], off offset:64
	global_store_dwordx4 v[160:161], v[96:99], off offset:128
	global_store_dwordx4 v[160:161], v[100:103], off offset:192
	v_mfma_f32_16x16x32_bf16 v[124:127], v[40:43], v[148:151], v[132:135]
	v_ashrrev_i32_e32 v157, 31, v156
	v_lshlrev_b64 v[88:89], 12, v[156:157]
	v_lshl_add_u64 v[88:89], s[48:49], 0, v[88:89]
	v_lshl_add_u64 v[88:89], v[88:89], 0, v[72:73]
	v_lshl_add_u64 v[112:113], v[88:89], 0, v[64:65]
	global_load_dwordx4 v[88:91], v[112:113], off
	global_load_dwordx4 v[96:99], v[112:113], off offset:64
	global_load_dwordx4 v[100:103], v[112:113], off offset:128
	global_load_dwordx4 v[104:107], v[112:113], off offset:192
	v_mfma_f32_16x16x32_bf16 v[92:95], v[36:39], v[148:151], v[136:139]
	s_waitcnt vmcnt(0)
	v_pk_mul_f32 v[88:89], v[88:89], s[16:17] op_sel_hi:[1,0]
	v_mfma_f32_16x16x32_bf16 v[84:87], v[32:35], v[148:151], v[84:87]
	v_mul_f32_e64 v90, v90, s16
	v_mul_f32_e64 v91, v91, s16
	v_pk_mul_f32 v[96:97], v[96:97], s[16:17] op_sel_hi:[1,0]
	v_pk_mul_f32 v[98:99], v[98:99], s[16:17] op_sel_hi:[1,0]
	v_pk_mul_f32 v[100:101], v[100:101], s[16:17] op_sel_hi:[1,0]
	v_pk_mul_f32 v[102:103], v[102:103], s[16:17] op_sel_hi:[1,0]
	v_pk_mul_f32 v[104:105], v[104:105], s[16:17] op_sel_hi:[1,0]
	v_pk_mul_f32 v[106:107], v[106:107], s[16:17] op_sel_hi:[1,0]
	v_pk_fma_f32 v[88:89], v[116:117], v[20:21], v[88:89]
	v_pk_fma_f32 v[90:91], v[118:119], v[22:23], v[90:91]
	v_pk_fma_f32 v[96:97], v[124:125], v[0:1], v[96:97]
	v_pk_fma_f32 v[98:99], v[126:127], v[2:3], v[98:99]
	v_pk_fma_f32 v[92:93], v[92:93], v[12:13], v[100:101]
	v_pk_fma_f32 v[94:95], v[94:95], v[14:15], v[102:103]
	v_pk_fma_f32 v[84:85], v[84:85], v[16:17], v[104:105]
	v_pk_fma_f32 v[86:87], v[86:87], v[18:19], v[106:107]
	global_store_dwordx4 v[112:113], v[88:91], off
	global_store_dwordx4 v[112:113], v[96:99], off offset:64
	global_store_dwordx4 v[112:113], v[92:95], off offset:128
	global_store_dwordx4 v[112:113], v[84:87], off offset:192
	v_mfma_f32_16x16x32_bf16 v[108:111], v[44:47], v[52:55], v[140:143]
	v_ashrrev_i32_e32 v159, 31, v158
	v_lshlrev_b64 v[84:85], 12, v[158:159]
	v_lshl_add_u64 v[84:85], s[48:49], 0, v[84:85]
	v_lshl_add_u64 v[84:85], v[84:85], 0, v[72:73]
	v_lshl_add_u64 v[104:105], v[84:85], 0, v[64:65]
	global_load_dwordx4 v[84:87], v[104:105], off
	global_load_dwordx4 v[92:95], v[104:105], off offset:64
	global_load_dwordx4 v[96:99], v[104:105], off offset:128
	global_load_dwordx4 v[100:103], v[104:105], off offset:192
	v_mfma_f32_16x16x32_bf16 v[88:91], v[40:43], v[52:55], v[152:155]
	v_mfma_f32_16x16x32_bf16 v[60:63], v[36:39], v[52:55], v[60:63]
	v_mfma_f32_16x16x32_bf16 v[52:55], v[32:35], v[52:55], v[56:59]
	v_mfma_f32_16x16x32_bf16 v[44:47], v[44:47], v[28:31], v[48:51]
	s_waitcnt vmcnt(0)
	s_nop 0
	v_pk_mul_f32 v[56:57], v[84:85], s[16:17] op_sel_hi:[1,0]
	v_pk_mul_f32 v[58:59], v[86:87], s[16:17] op_sel_hi:[1,0]
	v_pk_mul_f32 v[84:85], v[92:93], s[16:17] op_sel_hi:[1,0]
	v_pk_mul_f32 v[86:87], v[94:95], s[16:17] op_sel_hi:[1,0]
	v_pk_mul_f32 v[92:93], v[96:97], s[16:17] op_sel_hi:[1,0]
	v_pk_mul_f32 v[94:95], v[98:99], s[16:17] op_sel_hi:[1,0]
	v_pk_mul_f32 v[96:97], v[100:101], s[16:17] op_sel_hi:[1,0]
	v_pk_mul_f32 v[98:99], v[102:103], s[16:17] op_sel_hi:[1,0]
	v_pk_fma_f32 v[56:57], v[108:109], v[20:21], v[56:57]
	v_pk_fma_f32 v[58:59], v[110:111], v[22:23], v[58:59]
	v_pk_fma_f32 v[84:85], v[88:89], v[0:1], v[84:85]
	v_pk_fma_f32 v[86:87], v[90:91], v[2:3], v[86:87]
	v_pk_fma_f32 v[60:61], v[60:61], v[12:13], v[92:93]
	v_pk_fma_f32 v[62:63], v[62:63], v[14:15], v[94:95]
	v_pk_fma_f32 v[52:53], v[52:53], v[16:17], v[96:97]
	v_pk_fma_f32 v[54:55], v[54:55], v[18:19], v[98:99]
	global_store_dwordx4 v[104:105], v[56:59], off
	global_store_dwordx4 v[104:105], v[84:87], off offset:64
	global_store_dwordx4 v[104:105], v[60:63], off offset:128
	global_store_dwordx4 v[104:105], v[52:55], off offset:192
	v_mfma_f32_16x16x32_bf16 v[24:27], v[40:43], v[28:31], v[24:27]
	v_ashrrev_i32_e32 v75, 31, v74
	v_lshlrev_b64 v[52:53], 12, v[74:75]
	v_lshl_add_u64 v[52:53], s[48:49], 0, v[52:53]
	v_lshl_add_u64 v[52:53], v[52:53], 0, v[72:73]
	v_lshl_add_u64 v[60:61], v[52:53], 0, v[64:65]
	global_load_dwordx4 v[52:55], v[60:61], off
	global_load_dwordx4 v[48:51], v[60:61], off offset:64
	global_load_dwordx4 v[56:59], v[60:61], off offset:128
	global_load_dwordx4 v[40:43], v[60:61], off offset:192
	v_mfma_f32_16x16x32_bf16 v[4:7], v[36:39], v[28:31], v[4:7]
	s_add_i32 s17, s17, s34
	s_cmpk_gt_i32 s2, 0x9f
	s_waitcnt vmcnt(0)
	v_pk_mul_f32 v[36:37], v[56:57], s[16:17] op_sel_hi:[1,0]
	v_mfma_f32_16x16x32_bf16 v[8:11], v[32:35], v[28:31], v[8:11]
	v_mul_f32_e64 v28, v52, s16
	v_mul_f32_e64 v29, v53, s16
	v_pk_mul_f32 v[30:31], v[54:55], s[16:17] op_sel_hi:[1,0]
	v_pk_mul_f32 v[32:33], v[48:49], s[16:17] op_sel_hi:[1,0]
	v_pk_mul_f32 v[34:35], v[50:51], s[16:17] op_sel_hi:[1,0]
	v_pk_mul_f32 v[38:39], v[58:59], s[16:17] op_sel_hi:[1,0]
	v_pk_mul_f32 v[40:41], v[40:41], s[16:17] op_sel_hi:[1,0]
	v_pk_mul_f32 v[42:43], v[42:43], s[16:17] op_sel_hi:[1,0]
	v_pk_fma_f32 v[20:21], v[44:45], v[20:21], v[28:29]
	v_pk_fma_f32 v[22:23], v[46:47], v[22:23], v[30:31]
	v_pk_fma_f32 v[0:1], v[24:25], v[0:1], v[32:33]
	v_pk_fma_f32 v[2:3], v[26:27], v[2:3], v[34:35]
	v_pk_fma_f32 v[4:5], v[4:5], v[12:13], v[36:37]
	v_pk_fma_f32 v[6:7], v[6:7], v[14:15], v[38:39]
	v_pk_fma_f32 v[8:9], v[8:9], v[16:17], v[40:41]
	v_pk_fma_f32 v[10:11], v[10:11], v[18:19], v[42:43]
	global_store_dwordx4 v[60:61], v[20:23], off
	global_store_dwordx4 v[60:61], v[0:3], off offset:64
	global_store_dwordx4 v[60:61], v[4:7], off offset:128
	global_store_dwordx4 v[60:61], v[8:11], off offset:192
	s_cbranch_scc0 .LBB0_3062
